# lean in-proj epilogue issues next tile's first K-stage LDS-DMA early (warms L2/TLB); prologue variant re-issues it then stage 1
# speedup vs baseline: 1.0343x; 1.0019x over previous
.LBB0_211:
	s_mov_b32 s0, 1
	s_cmp_ge_i32 s4, s0
	s_mov_b64 s[0:1], -1
	s_cbranch_scc1 .LBB0_210
	s_mov_b64 s[0:1], s[12:13]
	s_mov_b64 s[0:1], s[14:15]
	s_mov_b64 s[0:1], s[16:17]
	s_mov_b64 s[0:1], s[18:19]
	s_mov_b64 s[0:1], s[20:21]
	s_mov_b64 s[0:1], s[22:23]
	s_mov_b64 s[0:1], s[24:25]
	v_readlane_b32 s36, v243, 22
	v_readlane_b32 s37, v243, 23
	v_readlane_b32 s38, v243, 24
	v_readlane_b32 s39, v243, 25
	s_mov_b64 s[28:29], s[26:27]
	s_mov_b64 s[94:95], s[36:37]
	s_mov_b64 s[0:1], s[38:39]
	v_readlane_b32 s40, v243, 26
	v_readlane_b32 s41, v243, 27
	s_mov_b64 s[0:1], s[40:41]
	v_readlane_b32 s42, v243, 28
	v_readlane_b32 s43, v243, 29
	s_mov_b64 s[0:1], s[42:43]
	v_readlane_b32 s44, v243, 30
	v_readlane_b32 s45, v243, 31
	s_mov_b64 s[0:1], s[44:45]
	v_readlane_b32 s46, v243, 32
	v_readlane_b32 s47, v243, 33
	s_mov_b64 s[0:1], s[46:47]
	v_readlane_b32 s48, v243, 34
	v_readlane_b32 s49, v243, 35
	v_readlane_b32 s50, v243, 36
	v_readlane_b32 s51, v243, 37
	s_mov_b64 s[84:85], s[48:49]
	s_mov_b64 s[86:87], s[50:51]
	s_mov_b64 s[0:1], s[52:53]
	s_mov_b64 s[0:1], s[54:55]
	s_mov_b64 s[0:1], s[56:57]
	s_mov_b64 s[0:1], s[58:59]
	s_mov_b64 s[2:3], s[60:61]
	v_writelane_b32 v242, s4, 14
	s_mov_b64 s[44:45], s[62:63]
	s_mov_b64 s[2:3], s[64:65]
	s_mov_b64 s[4:5], s[66:67]
	v_readlane_b32 s36, v243, 5
	v_readlane_b32 s37, v243, 6
	s_mov_b64 s[4:5], s[36:37]
	v_readlane_b32 s38, v243, 7
	v_readlane_b32 s39, v243, 8
	s_mov_b64 s[4:5], s[38:39]
	v_readlane_b32 s40, v243, 9
	v_readlane_b32 s41, v243, 10
	v_readlane_b32 s42, v243, 11
	v_readlane_b32 s43, v243, 12
	s_mov_b64 s[92:93], s[40:41]
	s_mov_b64 s[4:5], s[42:43]
	v_mov_b32_e32 v2, v200
	v_readlane_b32 s4, v243, 1
	v_readlane_b32 s5, v243, 2
	v_readlane_b32 s6, v243, 3
	v_readlane_b32 s7, v243, 4
	s_mov_b64 s[4:5], s[6:7]
	s_movk_i32 s38, 0x1e00
	v_readlane_b32 s4, v243, 15
	s_and_b32 s4, s4, 7
	s_cmp_lg_u32 s4, 0
	s_cselect_b64 s[40:41], -1, 0
	s_cmp_eq_u32 s4, 0
	s_cselect_b64 s[4:5], -1, 0
	s_and_b64 s[6:7], s[4:5], exec
	v_readlane_b32 s6, v243, 0
	v_readlane_b32 s7, v243, 41
	s_cselect_b32 s70, s7, s6
	s_movk_i32 s6, 0xf0
	s_cselect_b32 s71, s6, 0x780
	s_cmp_ge_i32 s70, s71
	s_cbranch_scc1 .LBB0_209
	s_mov_b32 s35, 0
	v_readlane_b32 s6, v242, 10
	s_add_u32 s42, s0, s6
	v_readlane_b32 s0, v242, 8
	s_addc_u32 s43, s1, s0
	s_and_b64 s[0:1], s[4:5], exec
	v_readlane_b32 s0, v243, 15
	v_readlane_b32 s1, v243, 42
	s_cselect_b32 s10, s1, s0
	v_ashrrev_i32_e32 v5, 6, v2
	v_bfe_u32 v6, v2, 2, 4
	s_movk_i32 s0, 0xffc0
	v_and_b32_e32 v9, 1, v5
	v_and_or_b32 v219, v2, s0, v6
	v_lshl_or_b32 v220, v5, 5, v6
	v_lshlrev_b32_e32 v221, 12, v5
	v_lshlrev_b32_e32 v222, 11, v5
	v_lshlrev_b32_e32 v6, 6, v2
	v_and_b32_e32 v131, 31, v2
	v_sub_u32_e32 v130, v221, v222
	v_and_b32_e32 v223, 0xffffe7c0, v6
	v_lshlrev_b32_e32 v6, 12, v9
	s_movk_i32 s0, 0x1880
	v_and_b32_e32 v0, 63, v2
	v_lshl_or_b32 v15, v131, 6, v6
	v_mad_u64_u32 v[6:7], s[0:1], v5, s0, v[130:131]
	v_cmp_gt_u32_e64 s[0:1], 32, v0
	v_cmp_lt_u32_e64 s[46:47], 31, v0
	v_lshlrev_b32_e32 v0, 7, v9
	v_lshlrev_b32_e32 v9, 4, v2
	v_bfe_u32 v3, v2, 5, 1
	v_lshrrev_b32_e32 v13, 2, v2
	v_lshl_add_u64 v[10:11], s[2:3], 0, v[0:1]
	v_and_b32_e32 v0, 0x70, v9
	v_bfe_u32 v14, v2, 2, 2
	v_lshl_add_u64 v[132:133], v[10:11], 0, v[0:1]
	v_or_b32_e32 v10, v6, v0
	v_bitop3_b32 v0, v3, v13, 3 bitop3:0x78
	v_lshlrev_b32_e32 v228, 4, v0
	v_bitop3_b32 v0, v3, v14, 2 bitop3:0x36
	s_movk_i32 s4, 0x90
	v_lshlrev_b32_e32 v229, 4, v0
	v_mul_u32_u24_e32 v0, 0x104, v3
	v_and_b32_e32 v8, 32, v2
	v_sub_u32_e32 v226, 0, v3
	v_mad_u32_u24 v5, v131, s4, v6
	v_lshlrev_b32_e32 v7, 6, v3
	v_mul_i32_i24_e32 v3, 0xffffff74, v131
	v_lshlrev_b32_e32 v0, 2, v0
	v_add3_u32 v230, v5, v3, v0
	v_mul_u32_u24_e32 v0, 0x104, v131
	v_lshlrev_b32_e32 v3, 2, v8
	v_lshrrev_b32_e32 v12, 4, v2
	v_add3_u32 v231, v6, v0, v3
	v_add_u32_e32 v0, 0x6000, v223
	v_bitop3_b32 v4, v2, v12, 3 bitop3:0x6c
	v_or_b32_e32 v232, v0, v228
	v_or_b32_e32 v234, v0, v229
	v_bitop3_b32 v0, v2, 3, v12 bitop3:0x48
	v_lshlrev_b32_e32 v4, 3, v4
	v_bfe_u32 v227, v2, 3, 3
	v_lshlrev_b32_e32 v0, 4, v0
	v_and_b32_e32 v4, 24, v4
	v_mul_u32_u24_e32 v11, 0x90, v227
	v_or_b32_e32 v3, 0xa000, v15
	v_and_or_b32 v0, v9, 64, v0
	v_or_b32_e32 v224, 0x4000, v15
	v_and_b32_e32 v225, 0xffffff80, v2
	v_or_b32_e32 v233, v3, v228
	v_or_b32_e32 v235, v3, v229
	v_lshl_add_u64 v[134:135], s[42:43], 0, v[0:1]
	v_lshl_add_u64 v[136:137], s[44:45], 0, v[0:1]
	v_lshlrev_b32_e32 v138, 1, v4
	v_lshlrev_b32_e32 v140, 2, v8
	v_add_u32_e32 v236, v5, v7
	v_add_u32_e32 v237, v10, v11
	s_branch .LBB0_215

.LBB0_219:
	s_lshr_b32 s2, s4, 2
	s_and_b32 s3, s4, 3
	s_lshl_b32 s3, s3, 3
	s_mov_b32 s6, 0x1001000a
	s_cmp_eq_u32 s2, 1
	s_cselect_b32 s6, 0x171b0611, s6
	s_cmp_eq_u32 s2, 2
	s_cselect_b32 s6, 0xe1c1d08, s6
	s_cmp_eq_u32 s2, 3
	s_cselect_b32 s6, 0x14090203, s6
	s_cmp_eq_u32 s2, 4
	s_cselect_b32 s6, 0x40f0512, s6
	s_cmp_eq_u32 s2, 5
	s_cselect_b32 s6, 0xc160b0d, s6
	s_cmp_eq_u32 s2, 6
	s_cselect_b32 s6, 0x191a1813, s6
	s_cmp_eq_u32 s2, 7
	s_cselect_b32 s6, 0x1507, s6
	s_lshr_b32 s6, s6, s3
	s_and_b32 s4, s6, 0xff
	s_lshl_b32 s5, s5, 8
	s_mov_b32 s32, s5
	v_add_u32_e32 v2, s5, v219
	v_ashrrev_i32_e32 v3, 31, v2
	v_lshlrev_b64 v[4:5], 11, v[2:3]
	v_and_b32_e32 v6, 0xfffe7000, v4
	v_mov_b32_e32 v7, v5
	v_lshlrev_b32_e32 v0, 6, v2
	s_lshl_b32 s6, s4, 7
	v_lshl_add_u64 v[6:7], s[44:45], 0, v[6:7]
	v_and_b32_e32 v0, 64, v0
	v_lshl_add_u64 v[2:3], v[6:7], 0, v[0:1]
	v_add_u32_e32 v6, s6, v220
	v_ashrrev_i32_e32 v7, 31, v6
	v_lshlrev_b64 v[8:9], 11, v[6:7]
	v_and_b32_e32 v10, 0xffff7000, v8
	v_mov_b32_e32 v11, v9
	v_lshlrev_b32_e32 v0, 6, v6
	v_lshl_add_u64 v[10:11], s[42:43], 0, v[10:11]
	v_and_b32_e32 v0, 64, v0
	v_mov_b32_e32 v139, v1
	v_lshl_add_u64 v[6:7], v[10:11], 0, v[0:1]
	v_readfirstlane_b32 s2, v221
	v_add_u32_e32 v0, 0x400, v221
	v_lshl_add_u64 v[2:3], v[2:3], 0, v[138:139]
	s_cmp_eq_u32 s35, 0x5aa51234
	s_cbranch_scc0 .Lmy_pf_novar
	v_lshl_add_u64 v[6:7], v[6:7], 0, v[138:139]
	v_mov_b32_e32 v0, v221
	s_mov_b64 s[2:3], 0x0
	v_readfirstlane_b32 s8, v0
	v_lshl_add_u64 v[10:11], v[174:175], 0, s[2:3]
	s_mov_b32 m0, s8
	s_nop 0
	global_load_lds_dwordx4 v[10:11], off
	v_add_u32_e32 v0, 0x400, v221
	s_mov_b64 s[2:3], 0x8000
	v_readfirstlane_b32 s8, v0
	v_lshl_add_u64 v[10:11], v[174:175], 0, s[2:3]
	s_mov_b32 m0, s8
	s_nop 0
	global_load_lds_dwordx4 v[10:11], off
	v_add_u32_e32 v0, 0x800, v221
	s_mov_b64 s[2:3], 0x10000
	v_readfirstlane_b32 s8, v0
	v_lshl_add_u64 v[10:11], v[174:175], 0, s[2:3]
	s_mov_b32 m0, s8
	s_nop 0
	global_load_lds_dwordx4 v[10:11], off
	v_add_u32_e32 v0, 0xc00, v221
	s_mov_b64 s[2:3], 0x18000
	v_readfirstlane_b32 s8, v0
	v_lshl_add_u64 v[10:11], v[174:175], 0, s[2:3]
	s_mov_b32 m0, s8
	s_nop 0
	global_load_lds_dwordx4 v[10:11], off
	v_add_u32_e32 v0, 0x4000, v130
	s_mov_b64 s[2:3], 0x0
	v_readfirstlane_b32 s8, v0
	v_lshl_add_u64 v[10:11], v[178:179], 0, s[2:3]
	s_mov_b32 m0, s8
	s_nop 0
	global_load_lds_dwordx4 v[10:11], off
	v_add_u32_e32 v0, 0x4400, v130
	s_mov_b64 s[2:3], 0x8000
	v_readfirstlane_b32 s8, v0
	v_lshl_add_u64 v[10:11], v[178:179], 0, s[2:3]
	s_mov_b32 m0, s8
	s_nop 0
	global_load_lds_dwordx4 v[10:11], off
	v_add_u32_e32 v0, 0x6000, v221
	s_mov_b64 s[2:3], 0x80
	v_readfirstlane_b32 s8, v0
	v_lshl_add_u64 v[10:11], v[2:3], 0, s[2:3]
	s_mov_b32 m0, s8
	s_nop 0
	global_load_lds_dwordx4 v[10:11], off
	v_add_u32_e32 v0, 0x6400, v221
	s_mov_b64 s[2:3], 0x8080
	v_readfirstlane_b32 s8, v0
	v_lshl_add_u64 v[10:11], v[2:3], 0, s[2:3]
	s_mov_b32 m0, s8
	s_nop 0
	global_load_lds_dwordx4 v[10:11], off
	v_add_u32_e32 v0, 0x6800, v221
	s_mov_b64 s[2:3], 0x10080
	v_readfirstlane_b32 s8, v0
	v_lshl_add_u64 v[10:11], v[2:3], 0, s[2:3]
	s_mov_b32 m0, s8
	s_nop 0
	global_load_lds_dwordx4 v[10:11], off
	v_add_u32_e32 v0, 0x6c00, v221
	s_mov_b64 s[2:3], 0x18080
	v_readfirstlane_b32 s8, v0
	v_lshl_add_u64 v[10:11], v[2:3], 0, s[2:3]
	s_mov_b32 m0, s8
	s_nop 0
	global_load_lds_dwordx4 v[10:11], off
	v_add_u32_e32 v0, 0xa000, v130
	s_mov_b64 s[2:3], 0x80
	v_readfirstlane_b32 s8, v0
	v_lshl_add_u64 v[10:11], v[6:7], 0, s[2:3]
	s_mov_b32 m0, s8
	s_nop 0
	global_load_lds_dwordx4 v[10:11], off
	v_add_u32_e32 v0, 0xa400, v130
	s_mov_b64 s[2:3], 0x8080
	v_readfirstlane_b32 s8, v0
	v_lshl_add_u64 v[10:11], v[6:7], 0, s[2:3]
	s_mov_b32 m0, s8
	s_nop 0
	global_load_lds_dwordx4 v[10:11], off
	v_and_b32_e32 v8, 0xfffff000, v8
	s_branch .Lmy_pf_join
.Lmy_pf_novar:
	s_nop 0
	s_mov_b32 m0, s2
	s_mov_b64 s[8:9], 0x8000
	v_readfirstlane_b32 s2, v0
	global_load_lds_dwordx4 v[2:3], off
	v_lshl_add_u64 v[10:11], v[2:3], 0, s[8:9]
	s_mov_b32 m0, s2
	s_mov_b64 s[2:3], 0x10000
	v_add_u32_e32 v0, 0x800, v221
	global_load_lds_dwordx4 v[10:11], off
	v_lshl_add_u64 v[10:11], v[2:3], 0, s[2:3]
	v_readfirstlane_b32 s2, v0
	s_mov_b32 m0, s2
	s_mov_b64 s[2:3], 0x18000
	v_add_u32_e32 v0, 0xc00, v221
	global_load_lds_dwordx4 v[10:11], off
	v_lshl_add_u64 v[10:11], v[2:3], 0, s[2:3]
	v_readfirstlane_b32 s2, v0
	v_add_u32_e32 v0, 0x4000, v130
	s_mov_b32 m0, s2
	v_readfirstlane_b32 s2, v0
	v_add_u32_e32 v0, 0x4400, v130
	v_lshl_add_u64 v[6:7], v[6:7], 0, v[138:139]
	global_load_lds_dwordx4 v[10:11], off
	s_mov_b32 m0, s2
	v_readfirstlane_b32 s2, v0
	v_add_u32_e32 v0, 0x6000, v221
	global_load_lds_dwordx4 v[6:7], off
	v_lshl_add_u64 v[10:11], v[6:7], 0, s[8:9]
	s_mov_b32 m0, s2
	s_mov_b64 s[8:9], 0x80
	v_readfirstlane_b32 s2, v0
	v_add_u32_e32 v0, 0x6400, v221
	global_load_lds_dwordx4 v[10:11], off
	v_lshl_add_u64 v[10:11], v[2:3], 0, s[8:9]
	s_mov_b32 m0, s2
	s_mov_b64 s[30:31], 0x8080
	v_readfirstlane_b32 s2, v0
	global_load_lds_dwordx4 v[10:11], off
	v_lshl_add_u64 v[10:11], v[2:3], 0, s[30:31]
	s_mov_b32 m0, s2
	s_mov_b64 s[2:3], 0x10080
	v_add_u32_e32 v0, 0x6800, v221
	global_load_lds_dwordx4 v[10:11], off
	v_lshl_add_u64 v[10:11], v[2:3], 0, s[2:3]
	v_readfirstlane_b32 s2, v0
	s_mov_b32 m0, s2
	s_mov_b64 s[2:3], 0x18080
	v_add_u32_e32 v0, 0x6c00, v221
	v_lshl_add_u64 v[2:3], v[2:3], 0, s[2:3]
	v_readfirstlane_b32 s2, v0
	v_add_u32_e32 v0, 0xa000, v130
	global_load_lds_dwordx4 v[10:11], off
	s_mov_b32 m0, s2
	v_readfirstlane_b32 s2, v0
	v_add_u32_e32 v0, 0xa400, v130
	global_load_lds_dwordx4 v[2:3], off
	v_lshl_add_u64 v[2:3], v[6:7], 0, s[8:9]
	s_mov_b32 m0, s2
	v_readfirstlane_b32 s2, v0
	global_load_lds_dwordx4 v[2:3], off
	v_lshl_add_u64 v[2:3], v[6:7], 0, s[30:31]
	s_mov_b32 m0, s2
	v_and_b32_e32 v8, 0xfffff000, v8
	global_load_lds_dwordx4 v[2:3], off
.Lmy_pf_join:
	v_and_b32_e32 v4, 0xfffff000, v4
	v_mov_b32_e32 v2, 0
	v_lshl_add_u64 v[142:143], v[134:135], 0, v[8:9]
	v_lshl_add_u64 v[144:145], v[136:137], 0, v[4:5]
	s_mov_b32 s7, 0
	s_mov_b64 s[2:3], 0
	v_mov_b32_e32 v3, v2
	v_mov_b32_e32 v4, v2
	v_mov_b32_e32 v5, v2
	v_mov_b32_e32 v6, v2
	v_mov_b32_e32 v7, v2
	v_mov_b32_e32 v8, v2
	v_mov_b32_e32 v9, v2
	v_mov_b32_e32 v10, v2
	v_mov_b32_e32 v11, v2
	v_mov_b32_e32 v12, v2
	v_mov_b32_e32 v13, v2
	v_mov_b32_e32 v14, v2
	v_mov_b32_e32 v15, v2
	v_mov_b32_e32 v16, v2
	v_mov_b32_e32 v17, v2
	v_mov_b32_e32 v18, v2
	v_mov_b32_e32 v19, v2
	v_mov_b32_e32 v20, v2
	v_mov_b32_e32 v21, v2
	v_mov_b32_e32 v22, v2
	v_mov_b32_e32 v23, v2
	v_mov_b32_e32 v24, v2
	v_mov_b32_e32 v25, v2
	v_mov_b32_e32 v26, v2
	v_mov_b32_e32 v27, v2
	v_mov_b32_e32 v28, v2
	v_mov_b32_e32 v29, v2
	v_mov_b32_e32 v30, v2
	v_mov_b32_e32 v31, v2
	v_mov_b32_e32 v32, v2
	v_mov_b32_e32 v33, v2
	v_mov_b32_e32 v34, v2
	v_mov_b32_e32 v35, v2
	v_mov_b32_e32 v36, v2
	v_mov_b32_e32 v37, v2
	v_mov_b32_e32 v38, v2
	v_mov_b32_e32 v39, v2
	v_mov_b32_e32 v40, v2
	v_mov_b32_e32 v41, v2
	v_mov_b32_e32 v42, v2
	v_mov_b32_e32 v43, v2
	v_mov_b32_e32 v44, v2
	v_mov_b32_e32 v45, v2
	v_mov_b32_e32 v46, v2
	v_mov_b32_e32 v47, v2
	v_mov_b32_e32 v48, v2
	v_mov_b32_e32 v49, v2
	s_nop 0
	v_mov_b32_e32 v50, v2
	v_mov_b32_e32 v51, v2
	v_mov_b32_e32 v52, v2
	v_mov_b32_e32 v53, v2
	v_mov_b32_e32 v54, v2
	v_mov_b32_e32 v55, v2
	v_mov_b32_e32 v56, v2
	v_mov_b32_e32 v57, v2
	v_mov_b32_e32 v58, v2
	v_mov_b32_e32 v59, v2
	v_mov_b32_e32 v60, v2
	v_mov_b32_e32 v61, v2
	v_mov_b32_e32 v62, v2
	v_mov_b32_e32 v63, v2
	v_mov_b32_e32 v64, v2
	v_mov_b32_e32 v65, v2
	v_mov_b32_e32 v66, v2
	v_mov_b32_e32 v67, v2
	v_mov_b32_e32 v68, v2
	v_mov_b32_e32 v69, v2
	v_mov_b32_e32 v70, v2
	v_mov_b32_e32 v71, v2
	v_mov_b32_e32 v72, v2
	v_mov_b32_e32 v73, v2
	v_mov_b32_e32 v74, v2
	v_mov_b32_e32 v75, v2
	v_mov_b32_e32 v76, v2
	v_mov_b32_e32 v77, v2
	v_mov_b32_e32 v78, v2
	v_mov_b32_e32 v79, v2
	v_mov_b32_e32 v80, v2
	v_mov_b32_e32 v81, v2
	v_mov_b32_e32 v82, v2
	v_mov_b32_e32 v83, v2
	v_mov_b32_e32 v84, v2
	v_mov_b32_e32 v85, v2
	v_mov_b32_e32 v86, v2
	v_mov_b32_e32 v87, v2
	v_mov_b32_e32 v88, v2
	v_mov_b32_e32 v89, v2
	v_mov_b32_e32 v90, v2
	v_mov_b32_e32 v91, v2
	v_mov_b32_e32 v92, v2
	v_mov_b32_e32 v93, v2
	v_mov_b32_e32 v94, v2
	v_mov_b32_e32 v95, v2
	v_mov_b32_e32 v96, v2
	v_mov_b32_e32 v97, v2
	v_mov_b32_e32 v98, v2
	v_mov_b32_e32 v99, v2
	v_mov_b32_e32 v100, v2
	v_mov_b32_e32 v101, v2
	v_mov_b32_e32 v102, v2
	v_mov_b32_e32 v103, v2
	v_mov_b32_e32 v104, v2
	v_mov_b32_e32 v105, v2
	v_mov_b32_e32 v106, v2
	v_mov_b32_e32 v107, v2
	v_mov_b32_e32 v108, v2
	v_mov_b32_e32 v109, v2
	v_mov_b32_e32 v110, v2
	v_mov_b32_e32 v111, v2
	v_mov_b32_e32 v112, v2
	v_mov_b32_e32 v113, v2
	v_mov_b32_e32 v114, v2
	v_mov_b32_e32 v115, v2
	v_mov_b32_e32 v116, v2
	v_mov_b32_e32 v117, v2
	v_mov_b32_e32 v118, v2
	v_mov_b32_e32 v119, v2
	v_mov_b32_e32 v120, v2
	v_mov_b32_e32 v121, v2
	v_mov_b32_e32 v122, v2
	v_mov_b32_e32 v123, v2
	v_mov_b32_e32 v124, v2
	v_mov_b32_e32 v125, v2
	v_mov_b32_e32 v126, v2
	v_mov_b32_e32 v127, v2
	v_mov_b32_e32 v128, v2
	v_mov_b32_e32 v129, v2
	s_mov_b32 s35, 0
.LBB0_220:
	s_cmp_gt_i32 s7, 0
	s_waitcnt vmcnt(6)
	s_cselect_b32 s8, -1, 2
	s_mul_i32 s9, s7, 0x6000
	s_waitcnt lgkmcnt(0)
	s_add_i32 s8, s8, s7
	v_add_u32_e32 v139, s9, v224
	v_add_u32_e32 v0, s9, v223
	s_mulk_i32 s8, 0x6000
	v_add_u32_e32 v154, v139, v228
	s_barrier
	v_lshl_add_u64 v[170:171], v[144:145], 0, s[2:3]
	v_add_u32_e32 v141, s8, v221
	v_lshl_add_u64 v[174:175], v[142:143], 0, s[2:3]
	v_add_u32_e32 v182, s8, v222
	v_add_u32_e32 v166, v0, v228
	ds_read_b128 v[146:149], v166
	ds_read_b128 v[150:153], v154
	ds_read_b128 v[154:157], v154 offset:2048
	v_lshl_add_u64 v[172:173], v[170:171], 0, s[88:89]
	v_lshl_add_u64 v[176:177], v[174:175], 0, s[88:89]
	v_add_u32_e32 v183, 0x4000, v182
	v_lshl_add_u64 v[178:179], v[170:171], 0, s[90:91]
	v_add_u32_e32 v184, 0x400, v141
	v_lshl_add_u64 v[180:181], v[170:171], 0, s[78:79]
	v_add_u32_e32 v185, 0x800, v141
	ds_read_b128 v[158:161], v166 offset:2048
	ds_read_b128 v[162:165], v166 offset:4096
	ds_read_b128 v[166:169], v166 offset:6144
	s_waitcnt lgkmcnt(3)
	s_setprio 1
	v_mfma_f32_32x32x16_bf16 v[114:129], v[146:149], v[150:153], v[114:129]
	v_mfma_f32_32x32x16_bf16 v[98:113], v[146:149], v[154:157], v[98:113]
	v_readfirstlane_b32 s8, v141
	s_mov_b32 m0, s8
	s_nop 0
	global_load_lds_dwordx4 v[172:173], off
	s_waitcnt lgkmcnt(2)
	v_mfma_f32_32x32x16_bf16 v[82:97], v[158:161], v[150:153], v[82:97]
	v_mfma_f32_32x32x16_bf16 v[66:81], v[158:161], v[154:157], v[66:81]
	v_readfirstlane_b32 s8, v184
	s_mov_b32 m0, s8
	s_nop 0
	global_load_lds_dwordx4 v[178:179], off
	s_waitcnt lgkmcnt(1)
	v_mfma_f32_32x32x16_bf16 v[50:65], v[162:165], v[150:153], v[50:65]
	v_mfma_f32_32x32x16_bf16 v[34:49], v[162:165], v[154:157], v[34:49]
	v_readfirstlane_b32 s8, v185
	s_mov_b32 m0, s8
	s_nop 0
	global_load_lds_dwordx4 v[180:181], off
	s_waitcnt lgkmcnt(0)
	v_mfma_f32_32x32x16_bf16 v[18:33], v[166:169], v[150:153], v[18:33]
	v_mfma_f32_32x32x16_bf16 v[2:17], v[166:169], v[154:157], v[2:17]
	s_setprio 0
	v_add_u32_e32 v0, v0, v229
	v_add_u32_e32 v139, v139, v229
	ds_read_b128 v[146:149], v0
	ds_read_b128 v[150:153], v139
	ds_read_b128 v[154:157], v139 offset:2048
	ds_read_b128 v[158:161], v0 offset:2048
	ds_read_b128 v[162:165], v0 offset:4096
	ds_read_b128 v[166:169], v0 offset:6144
	s_waitcnt lgkmcnt(3)
	s_setprio 1
	v_mfma_f32_32x32x16_bf16 v[114:129], v[146:149], v[150:153], v[114:129]
	v_mfma_f32_32x32x16_bf16 v[98:113], v[146:149], v[154:157], v[98:113]
	v_add_u32_e32 v0, 0xc00, v141
	v_lshl_add_u64 v[146:147], v[170:171], 0, s[76:77]
	v_readfirstlane_b32 s8, v0
	s_mov_b32 m0, s8
	s_nop 0
	global_load_lds_dwordx4 v[146:147], off
	s_waitcnt lgkmcnt(2)
	v_mfma_f32_32x32x16_bf16 v[82:97], v[158:161], v[150:153], v[82:97]
	v_mfma_f32_32x32x16_bf16 v[66:81], v[158:161], v[154:157], v[66:81]
	v_readfirstlane_b32 s8, v183
	s_mov_b32 m0, s8
	s_nop 0
	global_load_lds_dwordx4 v[176:177], off
	s_waitcnt lgkmcnt(1)
	v_mfma_f32_32x32x16_bf16 v[50:65], v[162:165], v[150:153], v[50:65]
	v_mfma_f32_32x32x16_bf16 v[34:49], v[162:165], v[154:157], v[34:49]
	v_add_u32_e32 v0, 0x4400, v182
	v_lshl_add_u64 v[146:147], v[174:175], 0, s[90:91]
	v_readfirstlane_b32 s8, v0
	s_mov_b32 m0, s8
	s_nop 0
	global_load_lds_dwordx4 v[146:147], off
	s_waitcnt lgkmcnt(0)
	v_mfma_f32_32x32x16_bf16 v[18:33], v[166:169], v[150:153], v[18:33]
	v_mfma_f32_32x32x16_bf16 v[2:17], v[166:169], v[154:157], v[2:17]
	s_setprio 0
	s_add_i32 s8, s7, 1
	s_cmp_lt_i32 s7, 2
	s_cselect_b32 s7, s8, 0
	s_add_u32 s2, s2, 0x80
	s_addc_u32 s3, s3, 0
	s_cmpk_eq_i32 s2, 0xf00
	s_cbranch_scc0 .LBB0_220
	s_waitcnt vmcnt(6)
	s_mul_i32 s2, s7, 0x6000
	s_waitcnt lgkmcnt(0)
	v_add_u32_e32 v139, s2, v224
	v_add_u32_e32 v0, s2, v223
	v_add_u32_e32 v150, v139, v228
	s_barrier
	v_add_u32_e32 v141, v0, v228
	ds_read_b128 v[142:145], v141
	ds_read_b128 v[146:149], v150
	ds_read_b128 v[150:153], v150 offset:2048
	ds_read_b128 v[154:157], v141 offset:2048
	ds_read_b128 v[158:161], v141 offset:4096
	ds_read_b128 v[162:165], v141 offset:6144
	s_waitcnt lgkmcnt(3)
	s_setprio 1
	v_mfma_f32_32x32x16_bf16 v[114:129], v[142:145], v[146:149], v[114:129]
	v_mfma_f32_32x32x16_bf16 v[98:113], v[142:145], v[150:153], v[98:113]
	s_waitcnt lgkmcnt(2)
	v_mfma_f32_32x32x16_bf16 v[82:97], v[154:157], v[146:149], v[82:97]
	v_mfma_f32_32x32x16_bf16 v[66:81], v[154:157], v[150:153], v[66:81]
	s_waitcnt lgkmcnt(1)
	v_mfma_f32_32x32x16_bf16 v[50:65], v[158:161], v[146:149], v[50:65]
	v_mfma_f32_32x32x16_bf16 v[34:49], v[158:161], v[150:153], v[34:49]
	s_waitcnt lgkmcnt(0)
	v_mfma_f32_32x32x16_bf16 v[18:33], v[162:165], v[146:149], v[18:33]
	v_mfma_f32_32x32x16_bf16 v[2:17], v[162:165], v[150:153], v[2:17]
	s_setprio 0
	v_add_u32_e32 v0, v0, v229
	v_add_u32_e32 v139, v139, v229
	ds_read_b128 v[142:145], v0
	ds_read_b128 v[146:149], v139
	ds_read_b128 v[150:153], v139 offset:2048
	ds_read_b128 v[154:157], v0 offset:2048
	ds_read_b128 v[158:161], v0 offset:4096
	ds_read_b128 v[162:165], v0 offset:6144
	s_waitcnt lgkmcnt(3)
	s_setprio 1
	v_mfma_f32_32x32x16_bf16 v[114:129], v[142:145], v[146:149], v[114:129]
	v_mfma_f32_32x32x16_bf16 v[98:113], v[142:145], v[150:153], v[98:113]
	s_waitcnt lgkmcnt(2)
	v_mfma_f32_32x32x16_bf16 v[82:97], v[154:157], v[146:149], v[82:97]
	v_mfma_f32_32x32x16_bf16 v[66:81], v[154:157], v[150:153], v[66:81]
	s_waitcnt lgkmcnt(1)
	v_mfma_f32_32x32x16_bf16 v[50:65], v[158:161], v[146:149], v[50:65]
	v_mfma_f32_32x32x16_bf16 v[34:49], v[158:161], v[150:153], v[34:49]
	s_waitcnt lgkmcnt(0)
	v_mfma_f32_32x32x16_bf16 v[18:33], v[162:165], v[146:149], v[18:33]
	v_mfma_f32_32x32x16_bf16 v[2:17], v[162:165], v[150:153], v[2:17]
	s_setprio 0
	s_waitcnt vmcnt(0)
	s_waitcnt lgkmcnt(0)
	s_barrier
	ds_read_b128 v[142:145], v232
	ds_read_b128 v[146:149], v233
	ds_read_b128 v[150:153], v233 offset:2048
	ds_read_b128 v[154:157], v232 offset:2048
	ds_read_b128 v[158:161], v232 offset:4096
	ds_read_b128 v[162:165], v232 offset:6144
	s_waitcnt lgkmcnt(3)
	s_setprio 1
	v_mfma_f32_32x32x16_bf16 v[114:129], v[142:145], v[146:149], v[114:129]
	v_mfma_f32_32x32x16_bf16 v[98:113], v[142:145], v[150:153], v[98:113]
	s_waitcnt lgkmcnt(2)
	v_mfma_f32_32x32x16_bf16 v[82:97], v[154:157], v[146:149], v[82:97]
	v_mfma_f32_32x32x16_bf16 v[66:81], v[154:157], v[150:153], v[66:81]
	s_waitcnt lgkmcnt(1)
	v_mfma_f32_32x32x16_bf16 v[50:65], v[158:161], v[146:149], v[50:65]
	v_mfma_f32_32x32x16_bf16 v[34:49], v[158:161], v[150:153], v[34:49]
	s_waitcnt lgkmcnt(0)
	v_mfma_f32_32x32x16_bf16 v[18:33], v[162:165], v[146:149], v[18:33]
	v_mfma_f32_32x32x16_bf16 v[2:17], v[162:165], v[150:153], v[2:17]
	s_setprio 0
	ds_read_b128 v[142:145], v234
	ds_read_b128 v[146:149], v235
	ds_read_b128 v[150:153], v235 offset:2048
	ds_read_b128 v[154:157], v234 offset:2048
	ds_read_b128 v[158:161], v234 offset:4096
	ds_read_b128 v[162:165], v234 offset:6144
	s_waitcnt lgkmcnt(3)
	s_setprio 1
	v_mfma_f32_32x32x16_bf16 v[114:129], v[142:145], v[146:149], v[114:129]
	v_mfma_f32_32x32x16_bf16 v[98:113], v[142:145], v[150:153], v[98:113]
	s_waitcnt lgkmcnt(2)
	v_mfma_f32_32x32x16_bf16 v[82:97], v[154:157], v[146:149], v[82:97]
	v_mfma_f32_32x32x16_bf16 v[66:81], v[154:157], v[150:153], v[66:81]
	s_waitcnt lgkmcnt(1)
	v_mfma_f32_32x32x16_bf16 v[50:65], v[158:161], v[146:149], v[50:65]
	v_mfma_f32_32x32x16_bf16 v[34:49], v[158:161], v[150:153], v[34:49]
	s_waitcnt lgkmcnt(0)
	v_mfma_f32_32x32x16_bf16 v[18:33], v[162:165], v[146:149], v[18:33]
	v_mfma_f32_32x32x16_bf16 v[2:17], v[162:165], v[150:153], v[2:17]
	s_setprio 0
	s_cmp_gt_i32 s4, 3
	s_cselect_b64 s[30:31], -1, 0
	s_add_i32 s2, s4, -8
	s_cmp_gt_u32 s2, 5
	s_cselect_b64 s[98:99], -1, 0
	s_and_b32 s2, s4, 0x7ffffffc
	s_cmp_lg_u32 s2, 20
	v_add_u32_e32 v238, s5, v225
	s_cselect_b64 s[2:3], -1, 0
	s_and_b32 s5, s4, 0x7ffffffe
	s_cmp_eq_u32 s5, 6
	s_cselect_b64 s[82:83], -1, 0
	s_sub_i32 s5, s4, 17
	v_add_u32_e32 v239, 0x800, v230
	v_add_u32_e32 v240, 0x1000, v230
	v_add_u32_e32 v241, 0x1800, v230
	s_waitcnt vmcnt(0) lgkmcnt(0)
	s_barrier
	s_mov_b32 s8, 0x0701c030
	s_mov_b32 s34, 0x380e00c0
	s_lshr_b32 s8, s8, s4
	s_lshr_b32 s34, s34, s4
	s_and_b32 s8, s8, 1
	s_and_b32 s34, s34, 1
	s_or_b32 s7, s8, s34
	s_cmp_eq_u32 s7, 0
	s_cbranch_scc1 .Lmy_g0e_std
	v_and_b32_e32 v151, 63, v200
	v_lshrrev_b32_e32 v150, 5, v151
	v_and_b32_e32 v146, 31, v151
	v_lshrrev_b32_e32 v147, 6, v200
	v_lshrrev_b32_e32 v152, 1, v147
	v_and_b32_e32 v148, 1, v147
	v_mul_u32_u24_e32 v147, 0x2200, v147
	v_add_u32_e32 v147, 0x6000, v147
	v_lshlrev_b32_e32 v146, 2, v146
	s_movk_i32 s6, 0x440
	v_mad_u32_u24 v146, v150, s6, v146
	v_add_u32_e32 v146, v146, v147
	v_lshrrev_b32_e32 v150, 4, v151
	v_and_b32_e32 v149, 15, v151
	s_movk_i32 s6, 0x110
	v_mad_u32_u24 v147, v150, s6, v147
	v_lshl_add_u32 v147, v149, 4, v147
	v_lshl_add_u32 v152, v152, 7, s32
	v_add_u32_e32 v152, v152, v150
	s_lshl_b32 s6, s4, 7
	v_lshl_add_u32 v148, v148, 6, s6
	v_lshl_add_u32 v148, v149, 2, v148
	v_lshlrev_b32_e32 v148, 1, v148
	v_mul_u32_u24_e32 v152, 0x1e00, v152
	v_add_u32_e32 v148, v148, v152
	s_mov_b64 s[8:9], s[64:65]
	s_add_i32 s70, s70, s10
	s_mov_b32 s35, 0
	s_cmp_lt_i32 s70, s71
	s_cbranch_scc0 .Lmy_pf_skip
	s_and_b64 vcc, exec, s[40:41]
	s_cbranch_vccnz .Lmy_pf_skip
	s_mul_hi_i32 s6, s70, 0x88888889
	s_add_i32 s6, s6, s70
	s_lshr_b32 s2, s6, 31
	s_ashr_i32 s3, s6, 5
	s_add_i32 s2, s3, s2
	s_mul_i32 s3, s2, 60
	s_ashr_i32 s4, s2, 1
	s_sub_i32 s3, s70, s3
	s_lshl_b32 s5, s4, 2
	v_readlane_b32 s6, v243, 43
	s_add_i32 s5, s5, s6
	s_and_b32 s6, s3, 3
	s_or_b32 s5, s5, s6
	s_xor_b32 s2, s4, s2
	s_bitcmp1_b32 s2, 0
	s_cselect_b32 s2, 15, 0
	s_ashr_i32 s3, s3, 2
	s_add_i32 s4, s2, s3
	s_lshr_b32 s2, s4, 2
	s_and_b32 s3, s4, 3
	s_lshl_b32 s3, s3, 3
	s_mov_b32 s6, 0x1001000a
	s_cmp_eq_u32 s2, 1
	s_cselect_b32 s6, 0x171b0611, s6
	s_cmp_eq_u32 s2, 2
	s_cselect_b32 s6, 0xe1c1d08, s6
	s_cmp_eq_u32 s2, 3
	s_cselect_b32 s6, 0x14090203, s6
	s_cmp_eq_u32 s2, 4
	s_cselect_b32 s6, 0x40f0512, s6
	s_cmp_eq_u32 s2, 5
	s_cselect_b32 s6, 0xc160b0d, s6
	s_cmp_eq_u32 s2, 6
	s_cselect_b32 s6, 0x191a1813, s6
	s_cmp_eq_u32 s2, 7
	s_cselect_b32 s6, 0x1507, s6
	s_lshr_b32 s6, s6, s3
	s_and_b32 s4, s6, 0xff
	s_lshl_b32 s5, s5, 8
	s_lshl_b32 s6, s4, 7
	v_mov_b32_e32 v185, 0
	v_add_u32_e32 v174, s5, v219
	v_ashrrev_i32_e32 v175, 31, v174
	v_lshlrev_b64 v[176:177], 11, v[174:175]
	v_and_b32_e32 v178, 0xfffe7000, v176
	v_mov_b32_e32 v179, v177
	v_lshlrev_b32_e32 v184, 6, v174
	v_lshl_add_u64 v[178:179], s[44:45], 0, v[178:179]
	v_and_b32_e32 v184, 64, v184
	v_lshl_add_u64 v[174:175], v[178:179], 0, v[184:185]
	v_add_u32_e32 v178, s6, v220
	v_ashrrev_i32_e32 v179, 31, v178
	v_lshlrev_b64 v[180:181], 11, v[178:179]
	v_and_b32_e32 v182, 0xffff7000, v180
	v_mov_b32_e32 v183, v181
	v_lshlrev_b32_e32 v184, 6, v178
	v_lshl_add_u64 v[182:183], s[42:43], 0, v[182:183]
	v_and_b32_e32 v184, 64, v184
	v_mov_b32_e32 v139, v1
	v_lshl_add_u64 v[178:179], v[182:183], 0, v[184:185]
	v_lshl_add_u64 v[174:175], v[174:175], 0, v[138:139]
	v_lshl_add_u64 v[178:179], v[178:179], 0, v[138:139]
	v_mov_b32_e32 v184, v221
	v_readfirstlane_b32 s6, v184
	v_mov_b64_e32 v[182:183], v[174:175]
	s_mov_b32 m0, s6
	s_nop 0
	global_load_lds_dwordx4 v[182:183], off
	v_add_u32_e32 v184, 0x400, v221
	s_mov_b64 s[2:3], 0x8000
	v_readfirstlane_b32 s6, v184
	v_lshl_add_u64 v[182:183], v[174:175], 0, s[2:3]
	s_mov_b32 m0, s6
	s_nop 0
	global_load_lds_dwordx4 v[182:183], off
	v_add_u32_e32 v184, 0x800, v221
	s_mov_b64 s[2:3], 0x10000
	v_readfirstlane_b32 s6, v184
	v_lshl_add_u64 v[182:183], v[174:175], 0, s[2:3]
	s_mov_b32 m0, s6
	s_nop 0
	global_load_lds_dwordx4 v[182:183], off
	v_add_u32_e32 v184, 0xc00, v221
	s_mov_b64 s[2:3], 0x18000
	v_readfirstlane_b32 s6, v184
	v_lshl_add_u64 v[182:183], v[174:175], 0, s[2:3]
	s_mov_b32 m0, s6
	s_nop 0
	global_load_lds_dwordx4 v[182:183], off
	v_add_u32_e32 v184, 0x4000, v130
	v_readfirstlane_b32 s6, v184
	v_mov_b64_e32 v[182:183], v[178:179]
	s_mov_b32 m0, s6
	s_nop 0
	global_load_lds_dwordx4 v[182:183], off
	v_add_u32_e32 v184, 0x4400, v130
	s_mov_b64 s[2:3], 0x8000
	v_readfirstlane_b32 s6, v184
	v_lshl_add_u64 v[182:183], v[178:179], 0, s[2:3]
	s_mov_b32 m0, s6
	s_nop 0
	global_load_lds_dwordx4 v[182:183], off
	s_mov_b32 s35, 0x5aa51234
.Lmy_pf_skip:
	s_cmp_eq_u32 s34, 1
	s_cbranch_scc1 .Lmy_g0e_gate
	ds_write2_b32 v146, v114, v98 offset0:0 offset1:32
	ds_write2_b32 v146, v115, v99 offset0:68 offset1:100
	ds_write2_b32 v146, v116, v100 offset0:136 offset1:168
	ds_write2_b32 v146, v117, v101 offset0:204 offset1:236
	v_add_u32_e32 v146, 0x880, v146
	ds_write2_b32 v146, v118, v102 offset0:0 offset1:32
	ds_write2_b32 v146, v119, v103 offset0:68 offset1:100
	ds_write2_b32 v146, v120, v104 offset0:136 offset1:168
	ds_write2_b32 v146, v121, v105 offset0:204 offset1:236
	v_add_u32_e32 v146, 0x880, v146
	ds_write2_b32 v146, v122, v106 offset0:0 offset1:32
	ds_write2_b32 v146, v123, v107 offset0:68 offset1:100
	ds_write2_b32 v146, v124, v108 offset0:136 offset1:168
	ds_write2_b32 v146, v125, v109 offset0:204 offset1:236
	v_add_u32_e32 v146, 0x880, v146
	ds_write2_b32 v146, v126, v110 offset0:0 offset1:32
	ds_write2_b32 v146, v127, v111 offset0:68 offset1:100
	ds_write2_b32 v146, v128, v112 offset0:136 offset1:168
	ds_write2_b32 v146, v129, v113 offset0:204 offset1:236
	v_subrev_u32_e32 v146, 0x1980, v146
	s_waitcnt lgkmcnt(0)
	ds_read_b128 v[98:101], v147
	ds_read_b128 v[102:105], v147 offset:1088
	ds_read_b128 v[106:109], v147 offset:2176
	ds_read_b128 v[110:113], v147 offset:3264
	ds_read_b128 v[114:117], v147 offset:4352
	ds_read_b128 v[118:121], v147 offset:5440
	ds_read_b128 v[122:125], v147 offset:6528
	ds_read_b128 v[126:129], v147 offset:7616
	s_waitcnt lgkmcnt(7)
	v_cvt_pk_bf16_f32 v154, v98, v99
	v_cvt_pk_bf16_f32 v155, v100, v101
	global_store_dwordx2 v148, v[154:155], s[8:9]
	s_add_u32 s8, s8, 0x7800
	s_addc_u32 s9, s9, 0
	s_waitcnt lgkmcnt(6)
	v_cvt_pk_bf16_f32 v156, v102, v103
	v_cvt_pk_bf16_f32 v157, v104, v105
	global_store_dwordx2 v148, v[156:157], s[8:9]
	s_add_u32 s8, s8, 0x7800
	s_addc_u32 s9, s9, 0
	s_waitcnt lgkmcnt(5)
	v_cvt_pk_bf16_f32 v158, v106, v107
	v_cvt_pk_bf16_f32 v159, v108, v109
	global_store_dwordx2 v148, v[158:159], s[8:9]
	s_add_u32 s8, s8, 0x7800
	s_addc_u32 s9, s9, 0
	s_waitcnt lgkmcnt(4)
	v_cvt_pk_bf16_f32 v160, v110, v111
	v_cvt_pk_bf16_f32 v161, v112, v113
	global_store_dwordx2 v148, v[160:161], s[8:9]
	s_add_u32 s8, s8, 0x7800
	s_addc_u32 s9, s9, 0
	s_waitcnt lgkmcnt(3)
	v_cvt_pk_bf16_f32 v162, v114, v115
	v_cvt_pk_bf16_f32 v163, v116, v117
	global_store_dwordx2 v148, v[162:163], s[8:9]
	s_add_u32 s8, s8, 0x7800
	s_addc_u32 s9, s9, 0
	s_waitcnt lgkmcnt(2)
	v_cvt_pk_bf16_f32 v164, v118, v119
	v_cvt_pk_bf16_f32 v165, v120, v121
	global_store_dwordx2 v148, v[164:165], s[8:9]
	s_add_u32 s8, s8, 0x7800
	s_addc_u32 s9, s9, 0
	s_waitcnt lgkmcnt(1)
	v_cvt_pk_bf16_f32 v166, v122, v123
	v_cvt_pk_bf16_f32 v167, v124, v125
	global_store_dwordx2 v148, v[166:167], s[8:9]
	s_add_u32 s8, s8, 0x7800
	s_addc_u32 s9, s9, 0
	s_waitcnt lgkmcnt(0)
	v_cvt_pk_bf16_f32 v168, v126, v127
	v_cvt_pk_bf16_f32 v169, v128, v129
	global_store_dwordx2 v148, v[168:169], s[8:9]
	s_add_u32 s8, s8, 0x7800
	s_addc_u32 s9, s9, 0
	ds_write2_b32 v146, v82, v66 offset0:0 offset1:32
	ds_write2_b32 v146, v83, v67 offset0:68 offset1:100
	ds_write2_b32 v146, v84, v68 offset0:136 offset1:168
	ds_write2_b32 v146, v85, v69 offset0:204 offset1:236
	v_add_u32_e32 v146, 0x880, v146
	ds_write2_b32 v146, v86, v70 offset0:0 offset1:32
	ds_write2_b32 v146, v87, v71 offset0:68 offset1:100
	ds_write2_b32 v146, v88, v72 offset0:136 offset1:168
	ds_write2_b32 v146, v89, v73 offset0:204 offset1:236
	v_add_u32_e32 v146, 0x880, v146
	ds_write2_b32 v146, v90, v74 offset0:0 offset1:32
	ds_write2_b32 v146, v91, v75 offset0:68 offset1:100
	ds_write2_b32 v146, v92, v76 offset0:136 offset1:168
	ds_write2_b32 v146, v93, v77 offset0:204 offset1:236
	v_add_u32_e32 v146, 0x880, v146
	ds_write2_b32 v146, v94, v78 offset0:0 offset1:32
	ds_write2_b32 v146, v95, v79 offset0:68 offset1:100
	ds_write2_b32 v146, v96, v80 offset0:136 offset1:168
	ds_write2_b32 v146, v97, v81 offset0:204 offset1:236
	v_subrev_u32_e32 v146, 0x1980, v146
	s_waitcnt lgkmcnt(0)
	ds_read_b128 v[66:69], v147
	ds_read_b128 v[70:73], v147 offset:1088
	ds_read_b128 v[74:77], v147 offset:2176
	ds_read_b128 v[78:81], v147 offset:3264
	ds_read_b128 v[82:85], v147 offset:4352
	ds_read_b128 v[86:89], v147 offset:5440
	ds_read_b128 v[90:93], v147 offset:6528
	ds_read_b128 v[94:97], v147 offset:7616
	s_waitcnt lgkmcnt(7)
	v_cvt_pk_bf16_f32 v154, v66, v67
	v_cvt_pk_bf16_f32 v155, v68, v69
	global_store_dwordx2 v148, v[154:155], s[8:9]
	s_add_u32 s8, s8, 0x7800
	s_addc_u32 s9, s9, 0
	s_waitcnt lgkmcnt(6)
	v_cvt_pk_bf16_f32 v156, v70, v71
	v_cvt_pk_bf16_f32 v157, v72, v73
	global_store_dwordx2 v148, v[156:157], s[8:9]
	s_add_u32 s8, s8, 0x7800
	s_addc_u32 s9, s9, 0
	s_waitcnt lgkmcnt(5)
	v_cvt_pk_bf16_f32 v158, v74, v75
	v_cvt_pk_bf16_f32 v159, v76, v77
	global_store_dwordx2 v148, v[158:159], s[8:9]
	s_add_u32 s8, s8, 0x7800
	s_addc_u32 s9, s9, 0
	s_waitcnt lgkmcnt(4)
	v_cvt_pk_bf16_f32 v160, v78, v79
	v_cvt_pk_bf16_f32 v161, v80, v81
	global_store_dwordx2 v148, v[160:161], s[8:9]
	s_add_u32 s8, s8, 0x7800
	s_addc_u32 s9, s9, 0
	s_waitcnt lgkmcnt(3)
	v_cvt_pk_bf16_f32 v162, v82, v83
	v_cvt_pk_bf16_f32 v163, v84, v85
	global_store_dwordx2 v148, v[162:163], s[8:9]
	s_add_u32 s8, s8, 0x7800
	s_addc_u32 s9, s9, 0
	s_waitcnt lgkmcnt(2)
	v_cvt_pk_bf16_f32 v164, v86, v87
	v_cvt_pk_bf16_f32 v165, v88, v89
	global_store_dwordx2 v148, v[164:165], s[8:9]
	s_add_u32 s8, s8, 0x7800
	s_addc_u32 s9, s9, 0
	s_waitcnt lgkmcnt(1)
	v_cvt_pk_bf16_f32 v166, v90, v91
	v_cvt_pk_bf16_f32 v167, v92, v93
	global_store_dwordx2 v148, v[166:167], s[8:9]
	s_add_u32 s8, s8, 0x7800
	s_addc_u32 s9, s9, 0
	s_waitcnt lgkmcnt(0)
	v_cvt_pk_bf16_f32 v168, v94, v95
	v_cvt_pk_bf16_f32 v169, v96, v97
	global_store_dwordx2 v148, v[168:169], s[8:9]
	s_add_u32 s8, s8, 0x7800
	s_addc_u32 s9, s9, 0
	ds_write2_b32 v146, v50, v34 offset0:0 offset1:32
	ds_write2_b32 v146, v51, v35 offset0:68 offset1:100
	ds_write2_b32 v146, v52, v36 offset0:136 offset1:168
	ds_write2_b32 v146, v53, v37 offset0:204 offset1:236
	v_add_u32_e32 v146, 0x880, v146
	ds_write2_b32 v146, v54, v38 offset0:0 offset1:32
	ds_write2_b32 v146, v55, v39 offset0:68 offset1:100
	ds_write2_b32 v146, v56, v40 offset0:136 offset1:168
	ds_write2_b32 v146, v57, v41 offset0:204 offset1:236
	v_add_u32_e32 v146, 0x880, v146
	ds_write2_b32 v146, v58, v42 offset0:0 offset1:32
	ds_write2_b32 v146, v59, v43 offset0:68 offset1:100
	ds_write2_b32 v146, v60, v44 offset0:136 offset1:168
	ds_write2_b32 v146, v61, v45 offset0:204 offset1:236
	v_add_u32_e32 v146, 0x880, v146
	ds_write2_b32 v146, v62, v46 offset0:0 offset1:32
	ds_write2_b32 v146, v63, v47 offset0:68 offset1:100
	ds_write2_b32 v146, v64, v48 offset0:136 offset1:168
	ds_write2_b32 v146, v65, v49 offset0:204 offset1:236
	v_subrev_u32_e32 v146, 0x1980, v146
	s_waitcnt lgkmcnt(0)
	ds_read_b128 v[34:37], v147
	ds_read_b128 v[38:41], v147 offset:1088
	ds_read_b128 v[42:45], v147 offset:2176
	ds_read_b128 v[46:49], v147 offset:3264
	ds_read_b128 v[50:53], v147 offset:4352
	ds_read_b128 v[54:57], v147 offset:5440
	ds_read_b128 v[58:61], v147 offset:6528
	ds_read_b128 v[62:65], v147 offset:7616
	s_waitcnt lgkmcnt(7)
	v_cvt_pk_bf16_f32 v154, v34, v35
	v_cvt_pk_bf16_f32 v155, v36, v37
	global_store_dwordx2 v148, v[154:155], s[8:9]
	s_add_u32 s8, s8, 0x7800
	s_addc_u32 s9, s9, 0
	s_waitcnt lgkmcnt(6)
	v_cvt_pk_bf16_f32 v156, v38, v39
	v_cvt_pk_bf16_f32 v157, v40, v41
	global_store_dwordx2 v148, v[156:157], s[8:9]
	s_add_u32 s8, s8, 0x7800
	s_addc_u32 s9, s9, 0
	s_waitcnt lgkmcnt(5)
	v_cvt_pk_bf16_f32 v158, v42, v43
	v_cvt_pk_bf16_f32 v159, v44, v45
	global_store_dwordx2 v148, v[158:159], s[8:9]
	s_add_u32 s8, s8, 0x7800
	s_addc_u32 s9, s9, 0
	s_waitcnt lgkmcnt(4)
	v_cvt_pk_bf16_f32 v160, v46, v47
	v_cvt_pk_bf16_f32 v161, v48, v49
	global_store_dwordx2 v148, v[160:161], s[8:9]
	s_add_u32 s8, s8, 0x7800
	s_addc_u32 s9, s9, 0
	s_waitcnt lgkmcnt(3)
	v_cvt_pk_bf16_f32 v162, v50, v51
	v_cvt_pk_bf16_f32 v163, v52, v53
	global_store_dwordx2 v148, v[162:163], s[8:9]
	s_add_u32 s8, s8, 0x7800
	s_addc_u32 s9, s9, 0
	s_waitcnt lgkmcnt(2)
	v_cvt_pk_bf16_f32 v164, v54, v55
	v_cvt_pk_bf16_f32 v165, v56, v57
	global_store_dwordx2 v148, v[164:165], s[8:9]
	s_add_u32 s8, s8, 0x7800
	s_addc_u32 s9, s9, 0
	s_waitcnt lgkmcnt(1)
	v_cvt_pk_bf16_f32 v166, v58, v59
	v_cvt_pk_bf16_f32 v167, v60, v61
	global_store_dwordx2 v148, v[166:167], s[8:9]
	s_add_u32 s8, s8, 0x7800
	s_addc_u32 s9, s9, 0
	s_waitcnt lgkmcnt(0)
	v_cvt_pk_bf16_f32 v168, v62, v63
	v_cvt_pk_bf16_f32 v169, v64, v65
	global_store_dwordx2 v148, v[168:169], s[8:9]
	s_add_u32 s8, s8, 0x7800
	s_addc_u32 s9, s9, 0
	ds_write2_b32 v146, v18, v2 offset0:0 offset1:32
	ds_write2_b32 v146, v19, v3 offset0:68 offset1:100
	ds_write2_b32 v146, v20, v4 offset0:136 offset1:168
	ds_write2_b32 v146, v21, v5 offset0:204 offset1:236
	v_add_u32_e32 v146, 0x880, v146
	ds_write2_b32 v146, v22, v6 offset0:0 offset1:32
	ds_write2_b32 v146, v23, v7 offset0:68 offset1:100
	ds_write2_b32 v146, v24, v8 offset0:136 offset1:168
	ds_write2_b32 v146, v25, v9 offset0:204 offset1:236
	v_add_u32_e32 v146, 0x880, v146
	ds_write2_b32 v146, v26, v10 offset0:0 offset1:32
	ds_write2_b32 v146, v27, v11 offset0:68 offset1:100
	ds_write2_b32 v146, v28, v12 offset0:136 offset1:168
	ds_write2_b32 v146, v29, v13 offset0:204 offset1:236
	v_add_u32_e32 v146, 0x880, v146
	ds_write2_b32 v146, v30, v14 offset0:0 offset1:32
	ds_write2_b32 v146, v31, v15 offset0:68 offset1:100
	ds_write2_b32 v146, v32, v16 offset0:136 offset1:168
	ds_write2_b32 v146, v33, v17 offset0:204 offset1:236
	v_subrev_u32_e32 v146, 0x1980, v146
	s_waitcnt lgkmcnt(0)
	ds_read_b128 v[2:5], v147
	ds_read_b128 v[6:9], v147 offset:1088
	ds_read_b128 v[10:13], v147 offset:2176
	ds_read_b128 v[14:17], v147 offset:3264
	ds_read_b128 v[18:21], v147 offset:4352
	ds_read_b128 v[22:25], v147 offset:5440
	ds_read_b128 v[26:29], v147 offset:6528
	ds_read_b128 v[30:33], v147 offset:7616
	s_waitcnt lgkmcnt(7)
	v_cvt_pk_bf16_f32 v154, v2, v3
	v_cvt_pk_bf16_f32 v155, v4, v5
	global_store_dwordx2 v148, v[154:155], s[8:9]
	s_add_u32 s8, s8, 0x7800
	s_addc_u32 s9, s9, 0
	s_waitcnt lgkmcnt(6)
	v_cvt_pk_bf16_f32 v156, v6, v7
	v_cvt_pk_bf16_f32 v157, v8, v9
	global_store_dwordx2 v148, v[156:157], s[8:9]
	s_add_u32 s8, s8, 0x7800
	s_addc_u32 s9, s9, 0
	s_waitcnt lgkmcnt(5)
	v_cvt_pk_bf16_f32 v158, v10, v11
	v_cvt_pk_bf16_f32 v159, v12, v13
	global_store_dwordx2 v148, v[158:159], s[8:9]
	s_add_u32 s8, s8, 0x7800
	s_addc_u32 s9, s9, 0
	s_waitcnt lgkmcnt(4)
	v_cvt_pk_bf16_f32 v160, v14, v15
	v_cvt_pk_bf16_f32 v161, v16, v17
	global_store_dwordx2 v148, v[160:161], s[8:9]
	s_add_u32 s8, s8, 0x7800
	s_addc_u32 s9, s9, 0
	s_waitcnt lgkmcnt(3)
	v_cvt_pk_bf16_f32 v162, v18, v19
	v_cvt_pk_bf16_f32 v163, v20, v21
	global_store_dwordx2 v148, v[162:163], s[8:9]
	s_add_u32 s8, s8, 0x7800
	s_addc_u32 s9, s9, 0
	s_waitcnt lgkmcnt(2)
	v_cvt_pk_bf16_f32 v164, v22, v23
	v_cvt_pk_bf16_f32 v165, v24, v25
	global_store_dwordx2 v148, v[164:165], s[8:9]
	s_add_u32 s8, s8, 0x7800
	s_addc_u32 s9, s9, 0
	s_waitcnt lgkmcnt(1)
	v_cvt_pk_bf16_f32 v166, v26, v27
	v_cvt_pk_bf16_f32 v167, v28, v29
	global_store_dwordx2 v148, v[166:167], s[8:9]
	s_add_u32 s8, s8, 0x7800
	s_addc_u32 s9, s9, 0
	s_waitcnt lgkmcnt(0)
	v_cvt_pk_bf16_f32 v168, v30, v31
	v_cvt_pk_bf16_f32 v169, v32, v33
	global_store_dwordx2 v148, v[168:169], s[8:9]
	s_add_u32 s8, s8, 0x7800
	s_addc_u32 s9, s9, 0
	s_cmp_lt_i32 s70, s71
	s_waitcnt lgkmcnt(0)
	s_barrier
	s_cbranch_scc0 .LBB0_209
	s_branch .LBB0_215
.Lmy_g0e_gate:
	ds_write2_b32 v146, v114, v98 offset0:0 offset1:32
	ds_write2_b32 v146, v115, v99 offset0:68 offset1:100
	ds_write2_b32 v146, v116, v100 offset0:136 offset1:168
	ds_write2_b32 v146, v117, v101 offset0:204 offset1:236
	v_add_u32_e32 v146, 0x880, v146
	ds_write2_b32 v146, v118, v102 offset0:0 offset1:32
	ds_write2_b32 v146, v119, v103 offset0:68 offset1:100
	ds_write2_b32 v146, v120, v104 offset0:136 offset1:168
	ds_write2_b32 v146, v121, v105 offset0:204 offset1:236
	v_add_u32_e32 v146, 0x880, v146
	ds_write2_b32 v146, v122, v106 offset0:0 offset1:32
	ds_write2_b32 v146, v123, v107 offset0:68 offset1:100
	ds_write2_b32 v146, v124, v108 offset0:136 offset1:168
	ds_write2_b32 v146, v125, v109 offset0:204 offset1:236
	v_add_u32_e32 v146, 0x880, v146
	ds_write2_b32 v146, v126, v110 offset0:0 offset1:32
	ds_write2_b32 v146, v127, v111 offset0:68 offset1:100
	ds_write2_b32 v146, v128, v112 offset0:136 offset1:168
	ds_write2_b32 v146, v129, v113 offset0:204 offset1:236
	v_subrev_u32_e32 v146, 0x1980, v146
	s_waitcnt lgkmcnt(0)
	ds_read_b128 v[98:101], v147
	ds_read_b128 v[102:105], v147 offset:1088
	ds_read_b128 v[106:109], v147 offset:2176
	ds_read_b128 v[110:113], v147 offset:3264
	ds_read_b128 v[114:117], v147 offset:4352
	ds_read_b128 v[118:121], v147 offset:5440
	ds_read_b128 v[122:125], v147 offset:6528
	ds_read_b128 v[126:129], v147 offset:7616
	s_waitcnt lgkmcnt(7)
	v_mul_f32_e32 v170, 0xbfb8aa3b, v98
	v_mul_f32_e32 v171, 0xbfb8aa3b, v99
	v_mul_f32_e32 v172, 0xbfb8aa3b, v100
	v_mul_f32_e32 v173, 0xbfb8aa3b, v101
	v_exp_f32_e32 v170, v170
	v_exp_f32_e32 v171, v171
	v_exp_f32_e32 v172, v172
	v_exp_f32_e32 v173, v173
	v_add_f32_e32 v170, 1.0, v170
	v_add_f32_e32 v171, 1.0, v171
	v_add_f32_e32 v172, 1.0, v172
	v_add_f32_e32 v173, 1.0, v173
	v_rcp_f32_e32 v170, v170
	v_rcp_f32_e32 v171, v171
	v_rcp_f32_e32 v172, v172
	v_rcp_f32_e32 v173, v173
	s_nop 0
	v_mul_f32_e32 v98, v98, v170
	v_mul_f32_e32 v99, v99, v171
	v_mul_f32_e32 v100, v100, v172
	v_mul_f32_e32 v101, v101, v173
	v_cvt_pk_bf16_f32 v154, v98, v99
	v_cvt_pk_bf16_f32 v155, v100, v101
	global_store_dwordx2 v148, v[154:155], s[8:9]
	s_add_u32 s8, s8, 0x7800
	s_addc_u32 s9, s9, 0
	s_waitcnt lgkmcnt(6)
	v_mul_f32_e32 v170, 0xbfb8aa3b, v102
	v_mul_f32_e32 v171, 0xbfb8aa3b, v103
	v_mul_f32_e32 v172, 0xbfb8aa3b, v104
	v_mul_f32_e32 v173, 0xbfb8aa3b, v105
	v_exp_f32_e32 v170, v170
	v_exp_f32_e32 v171, v171
	v_exp_f32_e32 v172, v172
	v_exp_f32_e32 v173, v173
	v_add_f32_e32 v170, 1.0, v170
	v_add_f32_e32 v171, 1.0, v171
	v_add_f32_e32 v172, 1.0, v172
	v_add_f32_e32 v173, 1.0, v173
	v_rcp_f32_e32 v170, v170
	v_rcp_f32_e32 v171, v171
	v_rcp_f32_e32 v172, v172
	v_rcp_f32_e32 v173, v173
	s_nop 0
	v_mul_f32_e32 v102, v102, v170
	v_mul_f32_e32 v103, v103, v171
	v_mul_f32_e32 v104, v104, v172
	v_mul_f32_e32 v105, v105, v173
	v_cvt_pk_bf16_f32 v156, v102, v103
	v_cvt_pk_bf16_f32 v157, v104, v105
	global_store_dwordx2 v148, v[156:157], s[8:9]
	s_add_u32 s8, s8, 0x7800
	s_addc_u32 s9, s9, 0
	s_waitcnt lgkmcnt(5)
	v_mul_f32_e32 v170, 0xbfb8aa3b, v106
	v_mul_f32_e32 v171, 0xbfb8aa3b, v107
	v_mul_f32_e32 v172, 0xbfb8aa3b, v108
	v_mul_f32_e32 v173, 0xbfb8aa3b, v109
	v_exp_f32_e32 v170, v170
	v_exp_f32_e32 v171, v171
	v_exp_f32_e32 v172, v172
	v_exp_f32_e32 v173, v173
	v_add_f32_e32 v170, 1.0, v170
	v_add_f32_e32 v171, 1.0, v171
	v_add_f32_e32 v172, 1.0, v172
	v_add_f32_e32 v173, 1.0, v173
	v_rcp_f32_e32 v170, v170
	v_rcp_f32_e32 v171, v171
	v_rcp_f32_e32 v172, v172
	v_rcp_f32_e32 v173, v173
	s_nop 0
	v_mul_f32_e32 v106, v106, v170
	v_mul_f32_e32 v107, v107, v171
	v_mul_f32_e32 v108, v108, v172
	v_mul_f32_e32 v109, v109, v173
	v_cvt_pk_bf16_f32 v158, v106, v107
	v_cvt_pk_bf16_f32 v159, v108, v109
	global_store_dwordx2 v148, v[158:159], s[8:9]
	s_add_u32 s8, s8, 0x7800
	s_addc_u32 s9, s9, 0
	s_waitcnt lgkmcnt(4)
	v_mul_f32_e32 v170, 0xbfb8aa3b, v110
	v_mul_f32_e32 v171, 0xbfb8aa3b, v111
	v_mul_f32_e32 v172, 0xbfb8aa3b, v112
	v_mul_f32_e32 v173, 0xbfb8aa3b, v113
	v_exp_f32_e32 v170, v170
	v_exp_f32_e32 v171, v171
	v_exp_f32_e32 v172, v172
	v_exp_f32_e32 v173, v173
	v_add_f32_e32 v170, 1.0, v170
	v_add_f32_e32 v171, 1.0, v171
	v_add_f32_e32 v172, 1.0, v172
	v_add_f32_e32 v173, 1.0, v173
	v_rcp_f32_e32 v170, v170
	v_rcp_f32_e32 v171, v171
	v_rcp_f32_e32 v172, v172
	v_rcp_f32_e32 v173, v173
	s_nop 0
	v_mul_f32_e32 v110, v110, v170
	v_mul_f32_e32 v111, v111, v171
	v_mul_f32_e32 v112, v112, v172
	v_mul_f32_e32 v113, v113, v173
	v_cvt_pk_bf16_f32 v160, v110, v111
	v_cvt_pk_bf16_f32 v161, v112, v113
	global_store_dwordx2 v148, v[160:161], s[8:9]
	s_add_u32 s8, s8, 0x7800
	s_addc_u32 s9, s9, 0
	s_waitcnt lgkmcnt(3)
	v_mul_f32_e32 v170, 0xbfb8aa3b, v114
	v_mul_f32_e32 v171, 0xbfb8aa3b, v115
	v_mul_f32_e32 v172, 0xbfb8aa3b, v116
	v_mul_f32_e32 v173, 0xbfb8aa3b, v117
	v_exp_f32_e32 v170, v170
	v_exp_f32_e32 v171, v171
	v_exp_f32_e32 v172, v172
	v_exp_f32_e32 v173, v173
	v_add_f32_e32 v170, 1.0, v170
	v_add_f32_e32 v171, 1.0, v171
	v_add_f32_e32 v172, 1.0, v172
	v_add_f32_e32 v173, 1.0, v173
	v_rcp_f32_e32 v170, v170
	v_rcp_f32_e32 v171, v171
	v_rcp_f32_e32 v172, v172
	v_rcp_f32_e32 v173, v173
	s_nop 0
	v_mul_f32_e32 v114, v114, v170
	v_mul_f32_e32 v115, v115, v171
	v_mul_f32_e32 v116, v116, v172
	v_mul_f32_e32 v117, v117, v173
	v_cvt_pk_bf16_f32 v162, v114, v115
	v_cvt_pk_bf16_f32 v163, v116, v117
	global_store_dwordx2 v148, v[162:163], s[8:9]
	s_add_u32 s8, s8, 0x7800
	s_addc_u32 s9, s9, 0
	s_waitcnt lgkmcnt(2)
	v_mul_f32_e32 v170, 0xbfb8aa3b, v118
	v_mul_f32_e32 v171, 0xbfb8aa3b, v119
	v_mul_f32_e32 v172, 0xbfb8aa3b, v120
	v_mul_f32_e32 v173, 0xbfb8aa3b, v121
	v_exp_f32_e32 v170, v170
	v_exp_f32_e32 v171, v171
	v_exp_f32_e32 v172, v172
	v_exp_f32_e32 v173, v173
	v_add_f32_e32 v170, 1.0, v170
	v_add_f32_e32 v171, 1.0, v171
	v_add_f32_e32 v172, 1.0, v172
	v_add_f32_e32 v173, 1.0, v173
	v_rcp_f32_e32 v170, v170
	v_rcp_f32_e32 v171, v171
	v_rcp_f32_e32 v172, v172
	v_rcp_f32_e32 v173, v173
	s_nop 0
	v_mul_f32_e32 v118, v118, v170
	v_mul_f32_e32 v119, v119, v171
	v_mul_f32_e32 v120, v120, v172
	v_mul_f32_e32 v121, v121, v173
	v_cvt_pk_bf16_f32 v164, v118, v119
	v_cvt_pk_bf16_f32 v165, v120, v121
	global_store_dwordx2 v148, v[164:165], s[8:9]
	s_add_u32 s8, s8, 0x7800
	s_addc_u32 s9, s9, 0
	s_waitcnt lgkmcnt(1)
	v_mul_f32_e32 v170, 0xbfb8aa3b, v122
	v_mul_f32_e32 v171, 0xbfb8aa3b, v123
	v_mul_f32_e32 v172, 0xbfb8aa3b, v124
	v_mul_f32_e32 v173, 0xbfb8aa3b, v125
	v_exp_f32_e32 v170, v170
	v_exp_f32_e32 v171, v171
	v_exp_f32_e32 v172, v172
	v_exp_f32_e32 v173, v173
	v_add_f32_e32 v170, 1.0, v170
	v_add_f32_e32 v171, 1.0, v171
	v_add_f32_e32 v172, 1.0, v172
	v_add_f32_e32 v173, 1.0, v173
	v_rcp_f32_e32 v170, v170
	v_rcp_f32_e32 v171, v171
	v_rcp_f32_e32 v172, v172
	v_rcp_f32_e32 v173, v173
	s_nop 0
	v_mul_f32_e32 v122, v122, v170
	v_mul_f32_e32 v123, v123, v171
	v_mul_f32_e32 v124, v124, v172
	v_mul_f32_e32 v125, v125, v173
	v_cvt_pk_bf16_f32 v166, v122, v123
	v_cvt_pk_bf16_f32 v167, v124, v125
	global_store_dwordx2 v148, v[166:167], s[8:9]
	s_add_u32 s8, s8, 0x7800
	s_addc_u32 s9, s9, 0
	s_waitcnt lgkmcnt(0)
	v_mul_f32_e32 v170, 0xbfb8aa3b, v126
	v_mul_f32_e32 v171, 0xbfb8aa3b, v127
	v_mul_f32_e32 v172, 0xbfb8aa3b, v128
	v_mul_f32_e32 v173, 0xbfb8aa3b, v129
	v_exp_f32_e32 v170, v170
	v_exp_f32_e32 v171, v171
	v_exp_f32_e32 v172, v172
	v_exp_f32_e32 v173, v173
	v_add_f32_e32 v170, 1.0, v170
	v_add_f32_e32 v171, 1.0, v171
	v_add_f32_e32 v172, 1.0, v172
	v_add_f32_e32 v173, 1.0, v173
	v_rcp_f32_e32 v170, v170
	v_rcp_f32_e32 v171, v171
	v_rcp_f32_e32 v172, v172
	v_rcp_f32_e32 v173, v173
	s_nop 0
	v_mul_f32_e32 v126, v126, v170
	v_mul_f32_e32 v127, v127, v171
	v_mul_f32_e32 v128, v128, v172
	v_mul_f32_e32 v129, v129, v173
	v_cvt_pk_bf16_f32 v168, v126, v127
	v_cvt_pk_bf16_f32 v169, v128, v129
	global_store_dwordx2 v148, v[168:169], s[8:9]
	s_add_u32 s8, s8, 0x7800
	s_addc_u32 s9, s9, 0
	ds_write2_b32 v146, v82, v66 offset0:0 offset1:32
	ds_write2_b32 v146, v83, v67 offset0:68 offset1:100
	ds_write2_b32 v146, v84, v68 offset0:136 offset1:168
	ds_write2_b32 v146, v85, v69 offset0:204 offset1:236
	v_add_u32_e32 v146, 0x880, v146
	ds_write2_b32 v146, v86, v70 offset0:0 offset1:32
	ds_write2_b32 v146, v87, v71 offset0:68 offset1:100
	ds_write2_b32 v146, v88, v72 offset0:136 offset1:168
	ds_write2_b32 v146, v89, v73 offset0:204 offset1:236
	v_add_u32_e32 v146, 0x880, v146
	ds_write2_b32 v146, v90, v74 offset0:0 offset1:32
	ds_write2_b32 v146, v91, v75 offset0:68 offset1:100
	ds_write2_b32 v146, v92, v76 offset0:136 offset1:168
	ds_write2_b32 v146, v93, v77 offset0:204 offset1:236
	v_add_u32_e32 v146, 0x880, v146
	ds_write2_b32 v146, v94, v78 offset0:0 offset1:32
	ds_write2_b32 v146, v95, v79 offset0:68 offset1:100
	ds_write2_b32 v146, v96, v80 offset0:136 offset1:168
	ds_write2_b32 v146, v97, v81 offset0:204 offset1:236
	v_subrev_u32_e32 v146, 0x1980, v146
	s_waitcnt lgkmcnt(0)
	ds_read_b128 v[66:69], v147
	ds_read_b128 v[70:73], v147 offset:1088
	ds_read_b128 v[74:77], v147 offset:2176
	ds_read_b128 v[78:81], v147 offset:3264
	ds_read_b128 v[82:85], v147 offset:4352
	ds_read_b128 v[86:89], v147 offset:5440
	ds_read_b128 v[90:93], v147 offset:6528
	ds_read_b128 v[94:97], v147 offset:7616
	s_waitcnt lgkmcnt(7)
	v_mul_f32_e32 v170, 0xbfb8aa3b, v66
	v_mul_f32_e32 v171, 0xbfb8aa3b, v67
	v_mul_f32_e32 v172, 0xbfb8aa3b, v68
	v_mul_f32_e32 v173, 0xbfb8aa3b, v69
	v_exp_f32_e32 v170, v170
	v_exp_f32_e32 v171, v171
	v_exp_f32_e32 v172, v172
	v_exp_f32_e32 v173, v173
	v_add_f32_e32 v170, 1.0, v170
	v_add_f32_e32 v171, 1.0, v171
	v_add_f32_e32 v172, 1.0, v172
	v_add_f32_e32 v173, 1.0, v173
	v_rcp_f32_e32 v170, v170
	v_rcp_f32_e32 v171, v171
	v_rcp_f32_e32 v172, v172
	v_rcp_f32_e32 v173, v173
	s_nop 0
	v_mul_f32_e32 v66, v66, v170
	v_mul_f32_e32 v67, v67, v171
	v_mul_f32_e32 v68, v68, v172
	v_mul_f32_e32 v69, v69, v173
	v_cvt_pk_bf16_f32 v154, v66, v67
	v_cvt_pk_bf16_f32 v155, v68, v69
	global_store_dwordx2 v148, v[154:155], s[8:9]
	s_add_u32 s8, s8, 0x7800
	s_addc_u32 s9, s9, 0
	s_waitcnt lgkmcnt(6)
	v_mul_f32_e32 v170, 0xbfb8aa3b, v70
	v_mul_f32_e32 v171, 0xbfb8aa3b, v71
	v_mul_f32_e32 v172, 0xbfb8aa3b, v72
	v_mul_f32_e32 v173, 0xbfb8aa3b, v73
	v_exp_f32_e32 v170, v170
	v_exp_f32_e32 v171, v171
	v_exp_f32_e32 v172, v172
	v_exp_f32_e32 v173, v173
	v_add_f32_e32 v170, 1.0, v170
	v_add_f32_e32 v171, 1.0, v171
	v_add_f32_e32 v172, 1.0, v172
	v_add_f32_e32 v173, 1.0, v173
	v_rcp_f32_e32 v170, v170
	v_rcp_f32_e32 v171, v171
	v_rcp_f32_e32 v172, v172
	v_rcp_f32_e32 v173, v173
	s_nop 0
	v_mul_f32_e32 v70, v70, v170
	v_mul_f32_e32 v71, v71, v171
	v_mul_f32_e32 v72, v72, v172
	v_mul_f32_e32 v73, v73, v173
	v_cvt_pk_bf16_f32 v156, v70, v71
	v_cvt_pk_bf16_f32 v157, v72, v73
	global_store_dwordx2 v148, v[156:157], s[8:9]
	s_add_u32 s8, s8, 0x7800
	s_addc_u32 s9, s9, 0
	s_waitcnt lgkmcnt(5)
	v_mul_f32_e32 v170, 0xbfb8aa3b, v74
	v_mul_f32_e32 v171, 0xbfb8aa3b, v75
	v_mul_f32_e32 v172, 0xbfb8aa3b, v76
	v_mul_f32_e32 v173, 0xbfb8aa3b, v77
	v_exp_f32_e32 v170, v170
	v_exp_f32_e32 v171, v171
	v_exp_f32_e32 v172, v172
	v_exp_f32_e32 v173, v173
	v_add_f32_e32 v170, 1.0, v170
	v_add_f32_e32 v171, 1.0, v171
	v_add_f32_e32 v172, 1.0, v172
	v_add_f32_e32 v173, 1.0, v173
	v_rcp_f32_e32 v170, v170
	v_rcp_f32_e32 v171, v171
	v_rcp_f32_e32 v172, v172
	v_rcp_f32_e32 v173, v173
	s_nop 0
	v_mul_f32_e32 v74, v74, v170
	v_mul_f32_e32 v75, v75, v171
	v_mul_f32_e32 v76, v76, v172
	v_mul_f32_e32 v77, v77, v173
	v_cvt_pk_bf16_f32 v158, v74, v75
	v_cvt_pk_bf16_f32 v159, v76, v77
	global_store_dwordx2 v148, v[158:159], s[8:9]
	s_add_u32 s8, s8, 0x7800
	s_addc_u32 s9, s9, 0
	s_waitcnt lgkmcnt(4)
	v_mul_f32_e32 v170, 0xbfb8aa3b, v78
	v_mul_f32_e32 v171, 0xbfb8aa3b, v79
	v_mul_f32_e32 v172, 0xbfb8aa3b, v80
	v_mul_f32_e32 v173, 0xbfb8aa3b, v81
	v_exp_f32_e32 v170, v170
	v_exp_f32_e32 v171, v171
	v_exp_f32_e32 v172, v172
	v_exp_f32_e32 v173, v173
	v_add_f32_e32 v170, 1.0, v170
	v_add_f32_e32 v171, 1.0, v171
	v_add_f32_e32 v172, 1.0, v172
	v_add_f32_e32 v173, 1.0, v173
	v_rcp_f32_e32 v170, v170
	v_rcp_f32_e32 v171, v171
	v_rcp_f32_e32 v172, v172
	v_rcp_f32_e32 v173, v173
	s_nop 0
	v_mul_f32_e32 v78, v78, v170
	v_mul_f32_e32 v79, v79, v171
	v_mul_f32_e32 v80, v80, v172
	v_mul_f32_e32 v81, v81, v173
	v_cvt_pk_bf16_f32 v160, v78, v79
	v_cvt_pk_bf16_f32 v161, v80, v81
	global_store_dwordx2 v148, v[160:161], s[8:9]
	s_add_u32 s8, s8, 0x7800
	s_addc_u32 s9, s9, 0
	s_waitcnt lgkmcnt(3)
	v_mul_f32_e32 v170, 0xbfb8aa3b, v82
	v_mul_f32_e32 v171, 0xbfb8aa3b, v83
	v_mul_f32_e32 v172, 0xbfb8aa3b, v84
	v_mul_f32_e32 v173, 0xbfb8aa3b, v85
	v_exp_f32_e32 v170, v170
	v_exp_f32_e32 v171, v171
	v_exp_f32_e32 v172, v172
	v_exp_f32_e32 v173, v173
	v_add_f32_e32 v170, 1.0, v170
	v_add_f32_e32 v171, 1.0, v171
	v_add_f32_e32 v172, 1.0, v172
	v_add_f32_e32 v173, 1.0, v173
	v_rcp_f32_e32 v170, v170
	v_rcp_f32_e32 v171, v171
	v_rcp_f32_e32 v172, v172
	v_rcp_f32_e32 v173, v173
	s_nop 0
	v_mul_f32_e32 v82, v82, v170
	v_mul_f32_e32 v83, v83, v171
	v_mul_f32_e32 v84, v84, v172
	v_mul_f32_e32 v85, v85, v173
	v_cvt_pk_bf16_f32 v162, v82, v83
	v_cvt_pk_bf16_f32 v163, v84, v85
	global_store_dwordx2 v148, v[162:163], s[8:9]
	s_add_u32 s8, s8, 0x7800
	s_addc_u32 s9, s9, 0
	s_waitcnt lgkmcnt(2)
	v_mul_f32_e32 v170, 0xbfb8aa3b, v86
	v_mul_f32_e32 v171, 0xbfb8aa3b, v87
	v_mul_f32_e32 v172, 0xbfb8aa3b, v88
	v_mul_f32_e32 v173, 0xbfb8aa3b, v89
	v_exp_f32_e32 v170, v170
	v_exp_f32_e32 v171, v171
	v_exp_f32_e32 v172, v172
	v_exp_f32_e32 v173, v173
	v_add_f32_e32 v170, 1.0, v170
	v_add_f32_e32 v171, 1.0, v171
	v_add_f32_e32 v172, 1.0, v172
	v_add_f32_e32 v173, 1.0, v173
	v_rcp_f32_e32 v170, v170
	v_rcp_f32_e32 v171, v171
	v_rcp_f32_e32 v172, v172
	v_rcp_f32_e32 v173, v173
	s_nop 0
	v_mul_f32_e32 v86, v86, v170
	v_mul_f32_e32 v87, v87, v171
	v_mul_f32_e32 v88, v88, v172
	v_mul_f32_e32 v89, v89, v173
	v_cvt_pk_bf16_f32 v164, v86, v87
	v_cvt_pk_bf16_f32 v165, v88, v89
	global_store_dwordx2 v148, v[164:165], s[8:9]
	s_add_u32 s8, s8, 0x7800
	s_addc_u32 s9, s9, 0
	s_waitcnt lgkmcnt(1)
	v_mul_f32_e32 v170, 0xbfb8aa3b, v90
	v_mul_f32_e32 v171, 0xbfb8aa3b, v91
	v_mul_f32_e32 v172, 0xbfb8aa3b, v92
	v_mul_f32_e32 v173, 0xbfb8aa3b, v93
	v_exp_f32_e32 v170, v170
	v_exp_f32_e32 v171, v171
	v_exp_f32_e32 v172, v172
	v_exp_f32_e32 v173, v173
	v_add_f32_e32 v170, 1.0, v170
	v_add_f32_e32 v171, 1.0, v171
	v_add_f32_e32 v172, 1.0, v172
	v_add_f32_e32 v173, 1.0, v173
	v_rcp_f32_e32 v170, v170
	v_rcp_f32_e32 v171, v171
	v_rcp_f32_e32 v172, v172
	v_rcp_f32_e32 v173, v173
	s_nop 0
	v_mul_f32_e32 v90, v90, v170
	v_mul_f32_e32 v91, v91, v171
	v_mul_f32_e32 v92, v92, v172
	v_mul_f32_e32 v93, v93, v173
	v_cvt_pk_bf16_f32 v166, v90, v91
	v_cvt_pk_bf16_f32 v167, v92, v93
	global_store_dwordx2 v148, v[166:167], s[8:9]
	s_add_u32 s8, s8, 0x7800
	s_addc_u32 s9, s9, 0
	s_waitcnt lgkmcnt(0)
	v_mul_f32_e32 v170, 0xbfb8aa3b, v94
	v_mul_f32_e32 v171, 0xbfb8aa3b, v95
	v_mul_f32_e32 v172, 0xbfb8aa3b, v96
	v_mul_f32_e32 v173, 0xbfb8aa3b, v97
	v_exp_f32_e32 v170, v170
	v_exp_f32_e32 v171, v171
	v_exp_f32_e32 v172, v172
	v_exp_f32_e32 v173, v173
	v_add_f32_e32 v170, 1.0, v170
	v_add_f32_e32 v171, 1.0, v171
	v_add_f32_e32 v172, 1.0, v172
	v_add_f32_e32 v173, 1.0, v173
	v_rcp_f32_e32 v170, v170
	v_rcp_f32_e32 v171, v171
	v_rcp_f32_e32 v172, v172
	v_rcp_f32_e32 v173, v173
	s_nop 0
	v_mul_f32_e32 v94, v94, v170
	v_mul_f32_e32 v95, v95, v171
	v_mul_f32_e32 v96, v96, v172
	v_mul_f32_e32 v97, v97, v173
	v_cvt_pk_bf16_f32 v168, v94, v95
	v_cvt_pk_bf16_f32 v169, v96, v97
	global_store_dwordx2 v148, v[168:169], s[8:9]
	s_add_u32 s8, s8, 0x7800
	s_addc_u32 s9, s9, 0
	ds_write2_b32 v146, v50, v34 offset0:0 offset1:32
	ds_write2_b32 v146, v51, v35 offset0:68 offset1:100
	ds_write2_b32 v146, v52, v36 offset0:136 offset1:168
	ds_write2_b32 v146, v53, v37 offset0:204 offset1:236
	v_add_u32_e32 v146, 0x880, v146
	ds_write2_b32 v146, v54, v38 offset0:0 offset1:32
	ds_write2_b32 v146, v55, v39 offset0:68 offset1:100
	ds_write2_b32 v146, v56, v40 offset0:136 offset1:168
	ds_write2_b32 v146, v57, v41 offset0:204 offset1:236
	v_add_u32_e32 v146, 0x880, v146
	ds_write2_b32 v146, v58, v42 offset0:0 offset1:32
	ds_write2_b32 v146, v59, v43 offset0:68 offset1:100
	ds_write2_b32 v146, v60, v44 offset0:136 offset1:168
	ds_write2_b32 v146, v61, v45 offset0:204 offset1:236
	v_add_u32_e32 v146, 0x880, v146
	ds_write2_b32 v146, v62, v46 offset0:0 offset1:32
	ds_write2_b32 v146, v63, v47 offset0:68 offset1:100
	ds_write2_b32 v146, v64, v48 offset0:136 offset1:168
	ds_write2_b32 v146, v65, v49 offset0:204 offset1:236
	v_subrev_u32_e32 v146, 0x1980, v146
	s_waitcnt lgkmcnt(0)
	ds_read_b128 v[34:37], v147
	ds_read_b128 v[38:41], v147 offset:1088
	ds_read_b128 v[42:45], v147 offset:2176
	ds_read_b128 v[46:49], v147 offset:3264
	ds_read_b128 v[50:53], v147 offset:4352
	ds_read_b128 v[54:57], v147 offset:5440
	ds_read_b128 v[58:61], v147 offset:6528
	ds_read_b128 v[62:65], v147 offset:7616
	s_waitcnt lgkmcnt(7)
	v_mul_f32_e32 v170, 0xbfb8aa3b, v34
	v_mul_f32_e32 v171, 0xbfb8aa3b, v35
	v_mul_f32_e32 v172, 0xbfb8aa3b, v36
	v_mul_f32_e32 v173, 0xbfb8aa3b, v37
	v_exp_f32_e32 v170, v170
	v_exp_f32_e32 v171, v171
	v_exp_f32_e32 v172, v172
	v_exp_f32_e32 v173, v173
	v_add_f32_e32 v170, 1.0, v170
	v_add_f32_e32 v171, 1.0, v171
	v_add_f32_e32 v172, 1.0, v172
	v_add_f32_e32 v173, 1.0, v173
	v_rcp_f32_e32 v170, v170
	v_rcp_f32_e32 v171, v171
	v_rcp_f32_e32 v172, v172
	v_rcp_f32_e32 v173, v173
	s_nop 0
	v_mul_f32_e32 v34, v34, v170
	v_mul_f32_e32 v35, v35, v171
	v_mul_f32_e32 v36, v36, v172
	v_mul_f32_e32 v37, v37, v173
	v_cvt_pk_bf16_f32 v154, v34, v35
	v_cvt_pk_bf16_f32 v155, v36, v37
	global_store_dwordx2 v148, v[154:155], s[8:9]
	s_add_u32 s8, s8, 0x7800
	s_addc_u32 s9, s9, 0
	s_waitcnt lgkmcnt(6)
	v_mul_f32_e32 v170, 0xbfb8aa3b, v38
	v_mul_f32_e32 v171, 0xbfb8aa3b, v39
	v_mul_f32_e32 v172, 0xbfb8aa3b, v40
	v_mul_f32_e32 v173, 0xbfb8aa3b, v41
	v_exp_f32_e32 v170, v170
	v_exp_f32_e32 v171, v171
	v_exp_f32_e32 v172, v172
	v_exp_f32_e32 v173, v173
	v_add_f32_e32 v170, 1.0, v170
	v_add_f32_e32 v171, 1.0, v171
	v_add_f32_e32 v172, 1.0, v172
	v_add_f32_e32 v173, 1.0, v173
	v_rcp_f32_e32 v170, v170
	v_rcp_f32_e32 v171, v171
	v_rcp_f32_e32 v172, v172
	v_rcp_f32_e32 v173, v173
	s_nop 0
	v_mul_f32_e32 v38, v38, v170
	v_mul_f32_e32 v39, v39, v171
	v_mul_f32_e32 v40, v40, v172
	v_mul_f32_e32 v41, v41, v173
	v_cvt_pk_bf16_f32 v156, v38, v39
	v_cvt_pk_bf16_f32 v157, v40, v41
	global_store_dwordx2 v148, v[156:157], s[8:9]
	s_add_u32 s8, s8, 0x7800
	s_addc_u32 s9, s9, 0
	s_waitcnt lgkmcnt(5)
	v_mul_f32_e32 v170, 0xbfb8aa3b, v42
	v_mul_f32_e32 v171, 0xbfb8aa3b, v43
	v_mul_f32_e32 v172, 0xbfb8aa3b, v44
	v_mul_f32_e32 v173, 0xbfb8aa3b, v45
	v_exp_f32_e32 v170, v170
	v_exp_f32_e32 v171, v171
	v_exp_f32_e32 v172, v172
	v_exp_f32_e32 v173, v173
	v_add_f32_e32 v170, 1.0, v170
	v_add_f32_e32 v171, 1.0, v171
	v_add_f32_e32 v172, 1.0, v172
	v_add_f32_e32 v173, 1.0, v173
	v_rcp_f32_e32 v170, v170
	v_rcp_f32_e32 v171, v171
	v_rcp_f32_e32 v172, v172
	v_rcp_f32_e32 v173, v173
	s_nop 0
	v_mul_f32_e32 v42, v42, v170
	v_mul_f32_e32 v43, v43, v171
	v_mul_f32_e32 v44, v44, v172
	v_mul_f32_e32 v45, v45, v173
	v_cvt_pk_bf16_f32 v158, v42, v43
	v_cvt_pk_bf16_f32 v159, v44, v45
	global_store_dwordx2 v148, v[158:159], s[8:9]
	s_add_u32 s8, s8, 0x7800
	s_addc_u32 s9, s9, 0
	s_waitcnt lgkmcnt(4)
	v_mul_f32_e32 v170, 0xbfb8aa3b, v46
	v_mul_f32_e32 v171, 0xbfb8aa3b, v47
	v_mul_f32_e32 v172, 0xbfb8aa3b, v48
	v_mul_f32_e32 v173, 0xbfb8aa3b, v49
	v_exp_f32_e32 v170, v170
	v_exp_f32_e32 v171, v171
	v_exp_f32_e32 v172, v172
	v_exp_f32_e32 v173, v173
	v_add_f32_e32 v170, 1.0, v170
	v_add_f32_e32 v171, 1.0, v171
	v_add_f32_e32 v172, 1.0, v172
	v_add_f32_e32 v173, 1.0, v173
	v_rcp_f32_e32 v170, v170
	v_rcp_f32_e32 v171, v171
	v_rcp_f32_e32 v172, v172
	v_rcp_f32_e32 v173, v173
	s_nop 0
	v_mul_f32_e32 v46, v46, v170
	v_mul_f32_e32 v47, v47, v171
	v_mul_f32_e32 v48, v48, v172
	v_mul_f32_e32 v49, v49, v173
	v_cvt_pk_bf16_f32 v160, v46, v47
	v_cvt_pk_bf16_f32 v161, v48, v49
	global_store_dwordx2 v148, v[160:161], s[8:9]
	s_add_u32 s8, s8, 0x7800
	s_addc_u32 s9, s9, 0
	s_waitcnt lgkmcnt(3)
	v_mul_f32_e32 v170, 0xbfb8aa3b, v50
	v_mul_f32_e32 v171, 0xbfb8aa3b, v51
	v_mul_f32_e32 v172, 0xbfb8aa3b, v52
	v_mul_f32_e32 v173, 0xbfb8aa3b, v53
	v_exp_f32_e32 v170, v170
	v_exp_f32_e32 v171, v171
	v_exp_f32_e32 v172, v172
	v_exp_f32_e32 v173, v173
	v_add_f32_e32 v170, 1.0, v170
	v_add_f32_e32 v171, 1.0, v171
	v_add_f32_e32 v172, 1.0, v172
	v_add_f32_e32 v173, 1.0, v173
	v_rcp_f32_e32 v170, v170
	v_rcp_f32_e32 v171, v171
	v_rcp_f32_e32 v172, v172
	v_rcp_f32_e32 v173, v173
	s_nop 0
	v_mul_f32_e32 v50, v50, v170
	v_mul_f32_e32 v51, v51, v171
	v_mul_f32_e32 v52, v52, v172
	v_mul_f32_e32 v53, v53, v173
	v_cvt_pk_bf16_f32 v162, v50, v51
	v_cvt_pk_bf16_f32 v163, v52, v53
	global_store_dwordx2 v148, v[162:163], s[8:9]
	s_add_u32 s8, s8, 0x7800
	s_addc_u32 s9, s9, 0
	s_waitcnt lgkmcnt(2)
	v_mul_f32_e32 v170, 0xbfb8aa3b, v54
	v_mul_f32_e32 v171, 0xbfb8aa3b, v55
	v_mul_f32_e32 v172, 0xbfb8aa3b, v56
	v_mul_f32_e32 v173, 0xbfb8aa3b, v57
	v_exp_f32_e32 v170, v170
	v_exp_f32_e32 v171, v171
	v_exp_f32_e32 v172, v172
	v_exp_f32_e32 v173, v173
	v_add_f32_e32 v170, 1.0, v170
	v_add_f32_e32 v171, 1.0, v171
	v_add_f32_e32 v172, 1.0, v172
	v_add_f32_e32 v173, 1.0, v173
	v_rcp_f32_e32 v170, v170
	v_rcp_f32_e32 v171, v171
	v_rcp_f32_e32 v172, v172
	v_rcp_f32_e32 v173, v173
	s_nop 0
	v_mul_f32_e32 v54, v54, v170
	v_mul_f32_e32 v55, v55, v171
	v_mul_f32_e32 v56, v56, v172
	v_mul_f32_e32 v57, v57, v173
	v_cvt_pk_bf16_f32 v164, v54, v55
	v_cvt_pk_bf16_f32 v165, v56, v57
	global_store_dwordx2 v148, v[164:165], s[8:9]
	s_add_u32 s8, s8, 0x7800
	s_addc_u32 s9, s9, 0
	s_waitcnt lgkmcnt(1)
	v_mul_f32_e32 v170, 0xbfb8aa3b, v58
	v_mul_f32_e32 v171, 0xbfb8aa3b, v59
	v_mul_f32_e32 v172, 0xbfb8aa3b, v60
	v_mul_f32_e32 v173, 0xbfb8aa3b, v61
	v_exp_f32_e32 v170, v170
	v_exp_f32_e32 v171, v171
	v_exp_f32_e32 v172, v172
	v_exp_f32_e32 v173, v173
	v_add_f32_e32 v170, 1.0, v170
	v_add_f32_e32 v171, 1.0, v171
	v_add_f32_e32 v172, 1.0, v172
	v_add_f32_e32 v173, 1.0, v173
	v_rcp_f32_e32 v170, v170
	v_rcp_f32_e32 v171, v171
	v_rcp_f32_e32 v172, v172
	v_rcp_f32_e32 v173, v173
	s_nop 0
	v_mul_f32_e32 v58, v58, v170
	v_mul_f32_e32 v59, v59, v171
	v_mul_f32_e32 v60, v60, v172
	v_mul_f32_e32 v61, v61, v173
	v_cvt_pk_bf16_f32 v166, v58, v59
	v_cvt_pk_bf16_f32 v167, v60, v61
	global_store_dwordx2 v148, v[166:167], s[8:9]
	s_add_u32 s8, s8, 0x7800
	s_addc_u32 s9, s9, 0
	s_waitcnt lgkmcnt(0)
	v_mul_f32_e32 v170, 0xbfb8aa3b, v62
	v_mul_f32_e32 v171, 0xbfb8aa3b, v63
	v_mul_f32_e32 v172, 0xbfb8aa3b, v64
	v_mul_f32_e32 v173, 0xbfb8aa3b, v65
	v_exp_f32_e32 v170, v170
	v_exp_f32_e32 v171, v171
	v_exp_f32_e32 v172, v172
	v_exp_f32_e32 v173, v173
	v_add_f32_e32 v170, 1.0, v170
	v_add_f32_e32 v171, 1.0, v171
	v_add_f32_e32 v172, 1.0, v172
	v_add_f32_e32 v173, 1.0, v173
	v_rcp_f32_e32 v170, v170
	v_rcp_f32_e32 v171, v171
	v_rcp_f32_e32 v172, v172
	v_rcp_f32_e32 v173, v173
	s_nop 0
	v_mul_f32_e32 v62, v62, v170
	v_mul_f32_e32 v63, v63, v171
	v_mul_f32_e32 v64, v64, v172
	v_mul_f32_e32 v65, v65, v173
	v_cvt_pk_bf16_f32 v168, v62, v63
	v_cvt_pk_bf16_f32 v169, v64, v65
	global_store_dwordx2 v148, v[168:169], s[8:9]
	s_add_u32 s8, s8, 0x7800
	s_addc_u32 s9, s9, 0
	ds_write2_b32 v146, v18, v2 offset0:0 offset1:32
	ds_write2_b32 v146, v19, v3 offset0:68 offset1:100
	ds_write2_b32 v146, v20, v4 offset0:136 offset1:168
	ds_write2_b32 v146, v21, v5 offset0:204 offset1:236
	v_add_u32_e32 v146, 0x880, v146
	ds_write2_b32 v146, v22, v6 offset0:0 offset1:32
	ds_write2_b32 v146, v23, v7 offset0:68 offset1:100
	ds_write2_b32 v146, v24, v8 offset0:136 offset1:168
	ds_write2_b32 v146, v25, v9 offset0:204 offset1:236
	v_add_u32_e32 v146, 0x880, v146
	ds_write2_b32 v146, v26, v10 offset0:0 offset1:32
	ds_write2_b32 v146, v27, v11 offset0:68 offset1:100
	ds_write2_b32 v146, v28, v12 offset0:136 offset1:168
	ds_write2_b32 v146, v29, v13 offset0:204 offset1:236
	v_add_u32_e32 v146, 0x880, v146
	ds_write2_b32 v146, v30, v14 offset0:0 offset1:32
	ds_write2_b32 v146, v31, v15 offset0:68 offset1:100
	ds_write2_b32 v146, v32, v16 offset0:136 offset1:168
	ds_write2_b32 v146, v33, v17 offset0:204 offset1:236
	v_subrev_u32_e32 v146, 0x1980, v146
	s_waitcnt lgkmcnt(0)
	ds_read_b128 v[2:5], v147
	ds_read_b128 v[6:9], v147 offset:1088
	ds_read_b128 v[10:13], v147 offset:2176
	ds_read_b128 v[14:17], v147 offset:3264
	ds_read_b128 v[18:21], v147 offset:4352
	ds_read_b128 v[22:25], v147 offset:5440
	ds_read_b128 v[26:29], v147 offset:6528
	ds_read_b128 v[30:33], v147 offset:7616
	s_waitcnt lgkmcnt(7)
	v_mul_f32_e32 v170, 0xbfb8aa3b, v2
	v_mul_f32_e32 v171, 0xbfb8aa3b, v3
	v_mul_f32_e32 v172, 0xbfb8aa3b, v4
	v_mul_f32_e32 v173, 0xbfb8aa3b, v5
	v_exp_f32_e32 v170, v170
	v_exp_f32_e32 v171, v171
	v_exp_f32_e32 v172, v172
	v_exp_f32_e32 v173, v173
	v_add_f32_e32 v170, 1.0, v170
	v_add_f32_e32 v171, 1.0, v171
	v_add_f32_e32 v172, 1.0, v172
	v_add_f32_e32 v173, 1.0, v173
	v_rcp_f32_e32 v170, v170
	v_rcp_f32_e32 v171, v171
	v_rcp_f32_e32 v172, v172
	v_rcp_f32_e32 v173, v173
	s_nop 0
	v_mul_f32_e32 v2, v2, v170
	v_mul_f32_e32 v3, v3, v171
	v_mul_f32_e32 v4, v4, v172
	v_mul_f32_e32 v5, v5, v173
	v_cvt_pk_bf16_f32 v154, v2, v3
	v_cvt_pk_bf16_f32 v155, v4, v5
	global_store_dwordx2 v148, v[154:155], s[8:9]
	s_add_u32 s8, s8, 0x7800
	s_addc_u32 s9, s9, 0
	s_waitcnt lgkmcnt(6)
	v_mul_f32_e32 v170, 0xbfb8aa3b, v6
	v_mul_f32_e32 v171, 0xbfb8aa3b, v7
	v_mul_f32_e32 v172, 0xbfb8aa3b, v8
	v_mul_f32_e32 v173, 0xbfb8aa3b, v9
	v_exp_f32_e32 v170, v170
	v_exp_f32_e32 v171, v171
	v_exp_f32_e32 v172, v172
	v_exp_f32_e32 v173, v173
	v_add_f32_e32 v170, 1.0, v170
	v_add_f32_e32 v171, 1.0, v171
	v_add_f32_e32 v172, 1.0, v172
	v_add_f32_e32 v173, 1.0, v173
	v_rcp_f32_e32 v170, v170
	v_rcp_f32_e32 v171, v171
	v_rcp_f32_e32 v172, v172
	v_rcp_f32_e32 v173, v173
	s_nop 0
	v_mul_f32_e32 v6, v6, v170
	v_mul_f32_e32 v7, v7, v171
	v_mul_f32_e32 v8, v8, v172
	v_mul_f32_e32 v9, v9, v173
	v_cvt_pk_bf16_f32 v156, v6, v7
	v_cvt_pk_bf16_f32 v157, v8, v9
	global_store_dwordx2 v148, v[156:157], s[8:9]
	s_add_u32 s8, s8, 0x7800
	s_addc_u32 s9, s9, 0
	s_waitcnt lgkmcnt(5)
	v_mul_f32_e32 v170, 0xbfb8aa3b, v10
	v_mul_f32_e32 v171, 0xbfb8aa3b, v11
	v_mul_f32_e32 v172, 0xbfb8aa3b, v12
	v_mul_f32_e32 v173, 0xbfb8aa3b, v13
	v_exp_f32_e32 v170, v170
	v_exp_f32_e32 v171, v171
	v_exp_f32_e32 v172, v172
	v_exp_f32_e32 v173, v173
	v_add_f32_e32 v170, 1.0, v170
	v_add_f32_e32 v171, 1.0, v171
	v_add_f32_e32 v172, 1.0, v172
	v_add_f32_e32 v173, 1.0, v173
	v_rcp_f32_e32 v170, v170
	v_rcp_f32_e32 v171, v171
	v_rcp_f32_e32 v172, v172
	v_rcp_f32_e32 v173, v173
	s_nop 0
	v_mul_f32_e32 v10, v10, v170
	v_mul_f32_e32 v11, v11, v171
	v_mul_f32_e32 v12, v12, v172
	v_mul_f32_e32 v13, v13, v173
	v_cvt_pk_bf16_f32 v158, v10, v11
	v_cvt_pk_bf16_f32 v159, v12, v13
	global_store_dwordx2 v148, v[158:159], s[8:9]
	s_add_u32 s8, s8, 0x7800
	s_addc_u32 s9, s9, 0
	s_waitcnt lgkmcnt(4)
	v_mul_f32_e32 v170, 0xbfb8aa3b, v14
	v_mul_f32_e32 v171, 0xbfb8aa3b, v15
	v_mul_f32_e32 v172, 0xbfb8aa3b, v16
	v_mul_f32_e32 v173, 0xbfb8aa3b, v17
	v_exp_f32_e32 v170, v170
	v_exp_f32_e32 v171, v171
	v_exp_f32_e32 v172, v172
	v_exp_f32_e32 v173, v173
	v_add_f32_e32 v170, 1.0, v170
	v_add_f32_e32 v171, 1.0, v171
	v_add_f32_e32 v172, 1.0, v172
	v_add_f32_e32 v173, 1.0, v173
	v_rcp_f32_e32 v170, v170
	v_rcp_f32_e32 v171, v171
	v_rcp_f32_e32 v172, v172
	v_rcp_f32_e32 v173, v173
	s_nop 0
	v_mul_f32_e32 v14, v14, v170
	v_mul_f32_e32 v15, v15, v171
	v_mul_f32_e32 v16, v16, v172
	v_mul_f32_e32 v17, v17, v173
	v_cvt_pk_bf16_f32 v160, v14, v15
	v_cvt_pk_bf16_f32 v161, v16, v17
	global_store_dwordx2 v148, v[160:161], s[8:9]
	s_add_u32 s8, s8, 0x7800
	s_addc_u32 s9, s9, 0
	s_waitcnt lgkmcnt(3)
	v_mul_f32_e32 v170, 0xbfb8aa3b, v18
	v_mul_f32_e32 v171, 0xbfb8aa3b, v19
	v_mul_f32_e32 v172, 0xbfb8aa3b, v20
	v_mul_f32_e32 v173, 0xbfb8aa3b, v21
	v_exp_f32_e32 v170, v170
	v_exp_f32_e32 v171, v171
	v_exp_f32_e32 v172, v172
	v_exp_f32_e32 v173, v173
	v_add_f32_e32 v170, 1.0, v170
	v_add_f32_e32 v171, 1.0, v171
	v_add_f32_e32 v172, 1.0, v172
	v_add_f32_e32 v173, 1.0, v173
	v_rcp_f32_e32 v170, v170
	v_rcp_f32_e32 v171, v171
	v_rcp_f32_e32 v172, v172
	v_rcp_f32_e32 v173, v173
	s_nop 0
	v_mul_f32_e32 v18, v18, v170
	v_mul_f32_e32 v19, v19, v171
	v_mul_f32_e32 v20, v20, v172
	v_mul_f32_e32 v21, v21, v173
	v_cvt_pk_bf16_f32 v162, v18, v19
	v_cvt_pk_bf16_f32 v163, v20, v21
	global_store_dwordx2 v148, v[162:163], s[8:9]
	s_add_u32 s8, s8, 0x7800
	s_addc_u32 s9, s9, 0
	s_waitcnt lgkmcnt(2)
	v_mul_f32_e32 v170, 0xbfb8aa3b, v22
	v_mul_f32_e32 v171, 0xbfb8aa3b, v23
	v_mul_f32_e32 v172, 0xbfb8aa3b, v24
	v_mul_f32_e32 v173, 0xbfb8aa3b, v25
	v_exp_f32_e32 v170, v170
	v_exp_f32_e32 v171, v171
	v_exp_f32_e32 v172, v172
	v_exp_f32_e32 v173, v173
	v_add_f32_e32 v170, 1.0, v170
	v_add_f32_e32 v171, 1.0, v171
	v_add_f32_e32 v172, 1.0, v172
	v_add_f32_e32 v173, 1.0, v173
	v_rcp_f32_e32 v170, v170
	v_rcp_f32_e32 v171, v171
	v_rcp_f32_e32 v172, v172
	v_rcp_f32_e32 v173, v173
	s_nop 0
	v_mul_f32_e32 v22, v22, v170
	v_mul_f32_e32 v23, v23, v171
	v_mul_f32_e32 v24, v24, v172
	v_mul_f32_e32 v25, v25, v173
	v_cvt_pk_bf16_f32 v164, v22, v23
	v_cvt_pk_bf16_f32 v165, v24, v25
	global_store_dwordx2 v148, v[164:165], s[8:9]
	s_add_u32 s8, s8, 0x7800
	s_addc_u32 s9, s9, 0
	s_waitcnt lgkmcnt(1)
	v_mul_f32_e32 v170, 0xbfb8aa3b, v26
	v_mul_f32_e32 v171, 0xbfb8aa3b, v27
	v_mul_f32_e32 v172, 0xbfb8aa3b, v28
	v_mul_f32_e32 v173, 0xbfb8aa3b, v29
	v_exp_f32_e32 v170, v170
	v_exp_f32_e32 v171, v171
	v_exp_f32_e32 v172, v172
	v_exp_f32_e32 v173, v173
	v_add_f32_e32 v170, 1.0, v170
	v_add_f32_e32 v171, 1.0, v171
	v_add_f32_e32 v172, 1.0, v172
	v_add_f32_e32 v173, 1.0, v173
	v_rcp_f32_e32 v170, v170
	v_rcp_f32_e32 v171, v171
	v_rcp_f32_e32 v172, v172
	v_rcp_f32_e32 v173, v173
	s_nop 0
	v_mul_f32_e32 v26, v26, v170
	v_mul_f32_e32 v27, v27, v171
	v_mul_f32_e32 v28, v28, v172
	v_mul_f32_e32 v29, v29, v173
	v_cvt_pk_bf16_f32 v166, v26, v27
	v_cvt_pk_bf16_f32 v167, v28, v29
	global_store_dwordx2 v148, v[166:167], s[8:9]
	s_add_u32 s8, s8, 0x7800
	s_addc_u32 s9, s9, 0
	s_waitcnt lgkmcnt(0)
	v_mul_f32_e32 v170, 0xbfb8aa3b, v30
	v_mul_f32_e32 v171, 0xbfb8aa3b, v31
	v_mul_f32_e32 v172, 0xbfb8aa3b, v32
	v_mul_f32_e32 v173, 0xbfb8aa3b, v33
	v_exp_f32_e32 v170, v170
	v_exp_f32_e32 v171, v171
	v_exp_f32_e32 v172, v172
	v_exp_f32_e32 v173, v173
	v_add_f32_e32 v170, 1.0, v170
	v_add_f32_e32 v171, 1.0, v171
	v_add_f32_e32 v172, 1.0, v172
	v_add_f32_e32 v173, 1.0, v173
	v_rcp_f32_e32 v170, v170
	v_rcp_f32_e32 v171, v171
	v_rcp_f32_e32 v172, v172
	v_rcp_f32_e32 v173, v173
	s_nop 0
	v_mul_f32_e32 v30, v30, v170
	v_mul_f32_e32 v31, v31, v171
	v_mul_f32_e32 v32, v32, v172
	v_mul_f32_e32 v33, v33, v173
	v_cvt_pk_bf16_f32 v168, v30, v31
	v_cvt_pk_bf16_f32 v169, v32, v33
	global_store_dwordx2 v148, v[168:169], s[8:9]
	s_add_u32 s8, s8, 0x7800
	s_addc_u32 s9, s9, 0
	s_cmp_lt_i32 s70, s71
	s_waitcnt lgkmcnt(0)
	s_barrier
	s_cbranch_scc0 .LBB0_209
	s_branch .LBB0_215
